# v9 stack plus per-wave LDS stage writes of the GEMM epilogues without the surrounding lgkmcnt(0) waits (in-order LDS per wave; s_nop 1 keeps the store-data wait states)
# speedup vs baseline: 1.0038x; 1.0038x over previous
.LBB0_402:
	v_and_b32_e32 v80, 15, v139
	v_mov_b32_e32 v158, s53
	v_mad_u32_u24 v80, v80, s77, v158
	v_and_b32_e32 v139, -16, v139
	v_add_u32_e32 v158, v80, v139
	ds_write_b128 v158, v[68:71]
	ds_write_b128 v158, v[76:79] offset:64
	ds_write_b128 v158, v[90:93] offset:128
	ds_write_b128 v158, v[94:97] offset:192
	v_lshl_add_u32 v160, v157, 2, s53
	s_waitcnt lgkmcnt(0)
	ds_write_b128 v158, v[64:67] offset:4352
	ds_write_b128 v158, v[72:75] offset:4416
	ds_write_b128 v158, v[82:85] offset:4480
	ds_write_b128 v158, v[86:89] offset:4544
	v_mul_lo_u32 v64, v140, s77
	v_add_u32_e32 v139, v160, v64
	s_waitcnt lgkmcnt(0)
	ds_read_b128 v[64:67], v139
	ds_read_b128 v[74:77], v139 offset:16
	s_cmp_eq_u32 s100, 0
	s_cbranch_scc1 .Lg2_res0
	s_waitcnt vmcnt(0)
	v_lshlrev_b32_e32 v110, 16, v48
	v_and_b32_e32 v111, 0xffff0000, v48
	v_lshlrev_b32_e32 v112, 16, v49
	v_and_b32_e32 v113, 0xffff0000, v49
	v_lshlrev_b32_e32 v106, 16, v50
	v_and_b32_e32 v107, 0xffff0000, v50
	v_lshlrev_b32_e32 v108, 16, v51
	v_and_b32_e32 v109, 0xffff0000, v51
	v_lshlrev_b32_e32 v102, 16, v52
	v_and_b32_e32 v103, 0xffff0000, v52
	v_lshlrev_b32_e32 v104, 16, v53
	v_and_b32_e32 v105, 0xffff0000, v53
	v_lshlrev_b32_e32 v98, 16, v54
	v_and_b32_e32 v99, 0xffff0000, v54
	v_lshlrev_b32_e32 v100, 16, v55
	v_and_b32_e32 v101, 0xffff0000, v55
	v_lshlrev_b32_e32 v60, 16, v56
	v_and_b32_e32 v61, 0xffff0000, v56
	v_lshlrev_b32_e32 v62, 16, v57
	v_and_b32_e32 v63, 0xffff0000, v57
	v_lshlrev_b32_e32 v56, 16, v58
	v_and_b32_e32 v57, 0xffff0000, v58
	v_lshlrev_b32_e32 v58, 16, v59
	v_and_b32_e32 v59, 0xffff0000, v59
	v_lshlrev_b32_e32 v52, 16, v170
	v_and_b32_e32 v53, 0xffff0000, v170
	v_lshlrev_b32_e32 v54, 16, v171
	v_and_b32_e32 v55, 0xffff0000, v171
	v_lshlrev_b32_e32 v48, 16, v172
	v_and_b32_e32 v49, 0xffff0000, v172
	v_lshlrev_b32_e32 v50, 16, v173
	v_and_b32_e32 v51, 0xffff0000, v173

.LBB0_442:
	ds_write_b128 v158, v[20:23]
	ds_write_b128 v158, v[28:31] offset:64
	ds_write_b128 v158, v[40:43] offset:128
	ds_write_b128 v158, v[44:47] offset:192
	s_nop 1
	ds_write_b128 v158, v[16:19] offset:4352
	ds_write_b128 v158, v[24:27] offset:4416
	ds_write_b128 v158, v[32:35] offset:4480
	ds_write_b128 v158, v[36:39] offset:4544
	s_nop 1
	ds_read_b128 v[16:19], v139
	ds_read_b128 v[26:29], v139 offset:16
	s_cmp_eq_u32 s101, 0
	s_cbranch_scc1 .Lg2_res1
	s_waitcnt vmcnt(0)
	v_lshlrev_b32_e32 v76, 16, v48
	v_and_b32_e32 v77, 0xffff0000, v48
	v_lshlrev_b32_e32 v78, 16, v49
	v_and_b32_e32 v79, 0xffff0000, v49
	v_lshlrev_b32_e32 v72, 16, v50
	v_and_b32_e32 v73, 0xffff0000, v50
	v_lshlrev_b32_e32 v74, 16, v51
	v_and_b32_e32 v75, 0xffff0000, v51
	v_lshlrev_b32_e32 v68, 16, v52
	v_and_b32_e32 v69, 0xffff0000, v52
	v_lshlrev_b32_e32 v70, 16, v53
	v_and_b32_e32 v71, 0xffff0000, v53
	v_lshlrev_b32_e32 v64, 16, v54
	v_and_b32_e32 v65, 0xffff0000, v54
	v_lshlrev_b32_e32 v66, 16, v55
	v_and_b32_e32 v67, 0xffff0000, v55
	v_lshlrev_b32_e32 v60, 16, v56
	v_and_b32_e32 v61, 0xffff0000, v56
	v_lshlrev_b32_e32 v62, 16, v57
	v_and_b32_e32 v63, 0xffff0000, v57
	v_lshlrev_b32_e32 v56, 16, v58
	v_and_b32_e32 v57, 0xffff0000, v58
	v_lshlrev_b32_e32 v58, 16, v59
	v_and_b32_e32 v59, 0xffff0000, v59
	v_lshlrev_b32_e32 v52, 16, v98
	v_and_b32_e32 v53, 0xffff0000, v98
	v_lshlrev_b32_e32 v54, 16, v99
	v_and_b32_e32 v55, 0xffff0000, v99
	v_lshlrev_b32_e32 v48, 16, v100
	v_and_b32_e32 v49, 0xffff0000, v100
	v_lshlrev_b32_e32 v50, 16, v101
	v_and_b32_e32 v51, 0xffff0000, v101

.LBB0_579:
	v_mad_u32_u24 v80, v195, s77, v196
	ds_write_b128 v80, v[0:3]
	ds_write_b128 v80, v[4:7] offset:64
	ds_write_b128 v80, v[12:15] offset:128
	ds_write_b128 v80, v[152:155] offset:192
	s_nop 1

.LBB0_581:
	s_andn2_b64 vcc, exec, s[8:9]
	s_cbranch_vccnz .LBB0_588
	s_cmp_eq_u32 s58, 13
	s_mov_b64 s[8:9], -1
	s_cbranch_scc1 .LBB0_584
	v_mul_f32_e32 v80, 0xbfb8aa3b, v12
	v_exp_f32_e32 v80, v80
	v_mul_f32_e32 v82, 0xbfb8aa3b, v13
	v_exp_f32_e32 v83, v82
	v_mul_f32_e32 v0, 0xbfb8aa3b, v8
	v_add_f32_e32 v80, 1.0, v80
	v_rcp_f32_e32 v82, v80
	v_add_f32_e32 v80, 1.0, v83
	v_mul_f32_e32 v83, 0xbfb8aa3b, v14
	v_exp_f32_e32 v84, v83
	v_mul_f32_e32 v83, 0xbfb8aa3b, v15
	v_exp_f32_e32 v85, v83
	v_rcp_f32_e32 v83, v80
	v_add_f32_e32 v80, 1.0, v84
	v_rcp_f32_e32 v84, v80
	v_add_f32_e32 v80, 1.0, v85
	v_mul_f32_e32 v85, 0xbfb8aa3b, v152
	v_exp_f32_e32 v86, v85
	v_mul_f32_e32 v85, 0xbfb8aa3b, v153
	v_exp_f32_e32 v87, v85
	v_rcp_f32_e32 v85, v80
	v_add_f32_e32 v80, 1.0, v86
	v_mul_f32_e32 v1, 0xbfb8aa3b, v9
	v_mul_f32_e32 v2, 0xbfb8aa3b, v10
	v_mul_f32_e32 v3, 0xbfb8aa3b, v11
	v_rcp_f32_e32 v86, v80
	v_add_f32_e32 v80, 1.0, v87
	v_mul_f32_e32 v87, 0xbfb8aa3b, v154
	v_exp_f32_e32 v0, v0
	v_exp_f32_e32 v1, v1
	v_exp_f32_e32 v2, v2
	v_exp_f32_e32 v3, v3
	v_mul_f32_e32 v4, 0xbfb8aa3b, v156
	v_mul_f32_e32 v5, 0xbfb8aa3b, v157
	v_mul_f32_e32 v6, 0xbfb8aa3b, v158
	v_mul_f32_e32 v7, 0xbfb8aa3b, v159
	v_exp_f32_e32 v160, v87
	v_mul_f32_e32 v87, 0xbfb8aa3b, v155
	v_exp_f32_e32 v4, v4
	v_exp_f32_e32 v5, v5
	v_exp_f32_e32 v6, v6
	v_exp_f32_e32 v7, v7
	v_exp_f32_e32 v161, v87
	v_add_f32_e32 v0, 1.0, v0
	v_add_f32_e32 v1, 1.0, v1
	v_add_f32_e32 v2, 1.0, v2
	v_add_f32_e32 v3, 1.0, v3
	v_rcp_f32_e32 v87, v80
	v_add_f32_e32 v80, 1.0, v160
	v_rcp_f32_e32 v0, v0
	v_rcp_f32_e32 v1, v1
	v_rcp_f32_e32 v2, v2
	v_rcp_f32_e32 v3, v3
	v_add_f32_e32 v4, 1.0, v4
	v_add_f32_e32 v5, 1.0, v5
	v_add_f32_e32 v6, 1.0, v6
	v_add_f32_e32 v7, 1.0, v7
	v_rcp_f32_e32 v162, v80
	v_add_f32_e32 v80, 1.0, v161
	v_rcp_f32_e32 v4, v4
	v_rcp_f32_e32 v5, v5
	v_rcp_f32_e32 v6, v6
	v_rcp_f32_e32 v7, v7
	v_rcp_f32_e32 v163, v80
	v_pk_mul_f32 v[0:1], v[8:9], v[0:1]
	v_pk_mul_f32 v[2:3], v[10:11], v[2:3]
	v_mad_u32_u24 v80, v195, s77, v196
	v_pk_mul_f32 v[4:5], v[156:157], v[4:5]
	v_pk_mul_f32 v[6:7], v[158:159], v[6:7]
	v_pk_mul_f32 v[82:83], v[12:13], v[82:83]
	v_pk_mul_f32 v[84:85], v[14:15], v[84:85]
	v_pk_mul_f32 v[160:161], v[152:153], v[86:87]
	v_pk_mul_f32 v[162:163], v[154:155], v[162:163]
	ds_write_b128 v80, v[0:3]
	ds_write_b128 v80, v[4:7] offset:64
	ds_write_b128 v80, v[82:85] offset:128
	ds_write_b128 v80, v[160:163] offset:192
	s_nop 1
	s_mov_b64 s[8:9], 0

.LBB0_593:
	s_or_b64 exec, exec, s[8:9]
	s_waitcnt lgkmcnt(0)
	ds_read_b128 v[0:3], v201 offset:256
	ds_read_b128 v[4:7], v201 offset:320
	ds_read_b128 v[82:85], v201 offset:384
	ds_read_b128 v[160:163], v201 offset:448
	v_mad_u32_u24 v80, v195, s77, v196
	s_waitcnt lgkmcnt(0)
	v_pk_mul_f32 v[2:3], v[10:11], v[2:3]
	v_pk_mul_f32 v[0:1], v[8:9], v[0:1]
	v_pk_mul_f32 v[6:7], v[158:159], v[6:7]
	v_pk_mul_f32 v[4:5], v[156:157], v[4:5]
	v_pk_mul_f32 v[84:85], v[14:15], v[84:85]
	v_pk_mul_f32 v[82:83], v[12:13], v[82:83]
	v_pk_mul_f32 v[162:163], v[154:155], v[162:163]
	v_pk_mul_f32 v[160:161], v[152:153], v[160:161]
	ds_write_b128 v80, v[0:3]
	ds_write_b128 v80, v[4:7] offset:64
	ds_write_b128 v80, v[82:85] offset:128
	ds_write_b128 v80, v[160:163] offset:192
	s_nop 1
	v_mov_b32_e32 v80, v81
	v_mov_b32_e32 v82, v81
	v_mov_b32_e32 v83, v81
	v_mov_b32_e32 v84, v81
	v_mov_b32_e32 v85, v81
	v_mov_b32_e32 v86, v81
	v_mov_b32_e32 v87, v81
	v_mov_b64_e32 v[0:1], v[80:81]
	v_mov_b64_e32 v[2:3], v[82:83]
	v_mov_b64_e32 v[4:5], v[84:85]
	v_mov_b64_e32 v[6:7], v[86:87]
	s_mov_b64 s[8:9], 0

.LBB0_595:
	v_mad_u32_u24 v0, v195, s77, v196
	ds_write_b128 v0, v[8:11]
	ds_write_b128 v0, v[156:159] offset:64
	ds_write_b128 v0, v[12:15] offset:128
	ds_write_b128 v0, v[152:155] offset:192
	s_nop 1
	v_mov_b32_e32 v80, v81
	v_mov_b32_e32 v82, v81
	v_mov_b32_e32 v83, v81
	v_mov_b32_e32 v84, v81
	v_mov_b32_e32 v85, v81
	v_mov_b32_e32 v86, v81
	v_mov_b32_e32 v87, v81
	v_mov_b64_e32 v[0:1], v[80:81]
	v_mov_b64_e32 v[2:3], v[82:83]
	v_mov_b64_e32 v[4:5], v[84:85]
	v_mov_b64_e32 v[6:7], v[86:87]

.LBB0_601:
	v_mad_u32_u24 v80, v195, s77, v196
	ds_write_b128 v80, v[0:3]
	ds_write_b128 v80, v[82:85] offset:64
	ds_write_b128 v80, v[4:7] offset:128
	ds_write_b128 v80, v[160:163] offset:192
	s_nop 1
	v_mov_b32_e32 v80, v81
	v_mov_b32_e32 v82, v81
	v_mov_b32_e32 v83, v81
	v_mov_b32_e32 v84, v81
	v_mov_b32_e32 v85, v81
	v_mov_b32_e32 v86, v81
	v_mov_b32_e32 v87, v81
	v_mov_b64_e32 v[0:1], v[80:81]
	v_mov_b64_e32 v[2:3], v[82:83]
	v_mov_b64_e32 v[4:5], v[84:85]
	v_mov_b64_e32 v[6:7], v[86:87]

.LBB0_614:
	v_mad_u32_u24 v80, v195, s77, v196
	ds_write_b128 v80, v[0:3]
	ds_write_b128 v80, v[4:7] offset:64
	ds_write_b128 v80, v[82:85] offset:128
	ds_write_b128 v80, v[160:163] offset:192
	s_nop 1
	v_mov_b32_e32 v80, v81
	v_mov_b32_e32 v82, v81
	v_mov_b32_e32 v83, v81
	v_mov_b32_e32 v84, v81
	v_mov_b32_e32 v85, v81
	v_mov_b32_e32 v86, v81
	v_mov_b32_e32 v87, v81
	v_mov_b64_e32 v[0:1], v[80:81]
	v_mov_b64_e32 v[2:3], v[82:83]
	v_mov_b64_e32 v[4:5], v[84:85]
	v_mov_b64_e32 v[6:7], v[86:87]

.LBB0_632:
	v_mad_u32_u24 v80, v195, s77, v196
	ds_write_b128 v80, v[0:3]
	ds_write_b128 v80, v[82:85] offset:64
	ds_write_b128 v80, v[4:7] offset:128
	ds_write_b128 v80, v[160:163] offset:192
	s_nop 1
	v_mov_b32_e32 v80, v81
	v_mov_b32_e32 v82, v81
	v_mov_b32_e32 v83, v81
	v_mov_b32_e32 v84, v81
	v_mov_b32_e32 v85, v81
	v_mov_b32_e32 v86, v81
	v_mov_b32_e32 v87, v81
	v_mov_b64_e32 v[0:1], v[80:81]
	v_mov_b64_e32 v[2:3], v[82:83]
	v_mov_b64_e32 v[4:5], v[84:85]
	v_mov_b64_e32 v[6:7], v[86:87]
	s_cbranch_execz .LBB0_608
	s_branch .LBB0_609

.LBB0_635:
	v_mad_u32_u24 v80, v202, s77, v196
	ds_write_b128 v80, v[8:11]
	ds_write_b128 v80, v[12:15] offset:64
	ds_write_b128 v80, v[152:155] offset:128
	ds_write_b128 v80, v[156:159] offset:192
	v_readlane_b32 s36, v254, 37
	s_waitcnt lgkmcnt(0)
	v_readlane_b32 s37, v254, 38
	s_mov_b32 s3, s57
	s_andn2_b64 vcc, exec, s[36:37]
	s_cbranch_vccnz .LBB0_638
	s_lshl_b64 s[36:37], s[34:35], 15
	s_lshl_b32 s0, s2, 7
	v_ashrrev_i32_e32 v87, 31, v86
	s_add_u32 s36, s0, s36
	v_lshlrev_b64 v[8:9], 7, v[86:87]
	s_addc_u32 s37, 0, s37
	v_lshlrev_b32_e32 v10, 4, v194
	v_lshl_add_u64 v[8:9], s[36:37], 0, v[8:9]
	v_and_b32_e32 v10, 0x70, v10
	v_or_b32_e32 v8, v8, v10
	v_lshl_add_u64 v[8:9], s[42:43], 0, v[8:9]
	s_mov_b64 s[36:37], 0x4000000
	v_mul_lo_u32 v11, v86, s77
	v_lshl_add_u64 v[8:9], v[8:9], 0, s[36:37]
	v_add3_u32 v10, v11, v10, s97
	s_mov_b32 s0, 0

.LBB0_641:
	v_mov_b64_e32 v[14:15], v[6:7]
	s_andn2_b64 vcc, exec, s[44:45]
	v_mov_b64_e32 v[12:13], v[4:5]
	v_mov_b64_e32 v[10:11], v[2:3]
	v_mov_b64_e32 v[8:9], v[0:1]
	s_cbranch_vccnz .LBB0_650
	s_cmp_lg_u32 s58, 13
	s_mov_b64 s[44:45], -1
	s_cbranch_scc0 .LBB0_646
	v_mul_f32_e32 v80, 0xbfb8aa3b, v152
	v_exp_f32_e32 v80, v80
	v_mul_f32_e32 v87, 0xbfb8aa3b, v153
	v_exp_f32_e32 v87, v87
	v_mul_f32_e32 v165, 0xbfb8aa3b, v155
	v_add_f32_e32 v80, 1.0, v80
	v_rcp_f32_e32 v164, v80
	v_add_f32_e32 v80, 1.0, v87
	v_mul_f32_e32 v87, 0xbfb8aa3b, v154
	v_exp_f32_e32 v87, v87
	v_exp_f32_e32 v167, v165
	v_rcp_f32_e32 v165, v80
	v_mul_f32_e32 v8, 0xbfb8aa3b, v82
	v_add_f32_e32 v80, 1.0, v87
	v_mul_f32_e32 v87, 0xbfb8aa3b, v156
	v_rcp_f32_e32 v166, v80
	v_add_f32_e32 v80, 1.0, v167
	v_exp_f32_e32 v87, v87
	v_mul_f32_e32 v167, 0xbfb8aa3b, v157
	v_exp_f32_e32 v169, v167
	v_mul_f32_e32 v9, 0xbfb8aa3b, v83
	v_mul_f32_e32 v10, 0xbfb8aa3b, v84
	v_mul_f32_e32 v11, 0xbfb8aa3b, v85
	v_rcp_f32_e32 v167, v80
	v_add_f32_e32 v80, 1.0, v87
	v_mul_f32_e32 v87, 0xbfb8aa3b, v158
	v_exp_f32_e32 v8, v8
	v_exp_f32_e32 v9, v9
	v_exp_f32_e32 v10, v10
	v_exp_f32_e32 v11, v11
	v_mul_f32_e32 v12, 0xbfb8aa3b, v160
	v_mul_f32_e32 v13, 0xbfb8aa3b, v161
	v_mul_f32_e32 v14, 0xbfb8aa3b, v162
	v_mul_f32_e32 v15, 0xbfb8aa3b, v163
	v_rcp_f32_e32 v168, v80
	v_add_f32_e32 v80, 1.0, v169
	v_exp_f32_e32 v87, v87
	v_mul_f32_e32 v169, 0xbfb8aa3b, v159
	v_exp_f32_e32 v12, v12
	v_exp_f32_e32 v13, v13
	v_exp_f32_e32 v14, v14
	v_exp_f32_e32 v15, v15
	v_exp_f32_e32 v171, v169
	v_add_f32_e32 v8, 1.0, v8
	v_add_f32_e32 v9, 1.0, v9
	v_add_f32_e32 v10, 1.0, v10
	v_add_f32_e32 v11, 1.0, v11
	v_rcp_f32_e32 v169, v80
	v_add_f32_e32 v80, 1.0, v87
	v_rcp_f32_e32 v8, v8
	v_rcp_f32_e32 v9, v9
	v_rcp_f32_e32 v10, v10
	v_rcp_f32_e32 v11, v11
	v_add_f32_e32 v12, 1.0, v12
	v_add_f32_e32 v13, 1.0, v13
	v_add_f32_e32 v14, 1.0, v14
	v_add_f32_e32 v15, 1.0, v15
	v_rcp_f32_e32 v170, v80
	v_add_f32_e32 v80, 1.0, v171
	v_rcp_f32_e32 v12, v12
	v_rcp_f32_e32 v13, v13
	v_rcp_f32_e32 v14, v14
	v_rcp_f32_e32 v15, v15
	v_rcp_f32_e32 v171, v80
	v_pk_mul_f32 v[8:9], v[82:83], v[8:9]
	v_pk_mul_f32 v[10:11], v[84:85], v[10:11]
	v_mad_u32_u24 v80, v202, s77, v196
	v_ashrrev_i32_e32 v87, 31, v86
	v_readlane_b32 s36, v254, 54
	s_lshl_b32 s0, s16, 8
	v_readlane_b32 s3, v254, 33
	v_pk_mul_f32 v[12:13], v[160:161], v[12:13]
	v_pk_mul_f32 v[14:15], v[162:163], v[14:15]
	v_pk_mul_f32 v[164:165], v[152:153], v[164:165]
	v_pk_mul_f32 v[166:167], v[154:155], v[166:167]
	v_pk_mul_f32 v[168:169], v[156:157], v[168:169]
	v_pk_mul_f32 v[170:171], v[158:159], v[170:171]
	ds_write_b128 v80, v[8:11]
	ds_write_b128 v80, v[12:15] offset:64
	ds_write_b128 v80, v[164:167] offset:128
	ds_write_b128 v80, v[168:171] offset:192
	v_lshlrev_b64 v[8:9], 11, v[86:87]
	v_readlane_b32 s37, v254, 55
	s_or_b32 s60, s3, s0
	v_and_b32_e32 v10, 7, v194
	v_lshl_add_u64 v[8:9], v[8:9], 0, s[36:37]
	s_lshl_b64 s[36:37], s[60:61], 1
	v_lshlrev_b32_e32 v80, 4, v10
	s_add_u32 s36, s18, s36
	s_waitcnt lgkmcnt(0)
	v_lshl_add_u64 v[8:9], v[8:9], 0, v[80:81]
	s_addc_u32 s37, s19, s37
	v_lshl_add_u64 v[8:9], s[36:37], 0, v[8:9]
	s_mov_b64 s[36:37], 0x58ff200
	v_mul_lo_u32 v11, v86, s77
	v_lshlrev_b32_e32 v10, 5, v10
	v_lshl_add_u64 v[8:9], v[8:9], 0, s[36:37]
	v_add3_u32 v10, v11, v10, s50
	s_mov_b32 s0, 0
	s_mov_b64 s[36:37], 0x4000

.LBB0_654:
	s_or_b64 exec, exec, s[44:45]
	s_waitcnt lgkmcnt(0)
	ds_read_b128 v[8:11], v201 offset:256
	ds_read_b128 v[12:15], v201 offset:320
	ds_read_b128 v[164:167], v201 offset:384
	ds_read_b128 v[168:171], v201 offset:448
	s_lshl_b32 s0, s16, 8
	v_readlane_b32 s3, v254, 33
	s_waitcnt lgkmcnt(0)
	v_pk_mul_f32 v[10:11], v[84:85], v[10:11]
	v_pk_mul_f32 v[8:9], v[82:83], v[8:9]
	v_mad_u32_u24 v80, v202, s77, v196
	v_ashrrev_i32_e32 v87, 31, v86
	s_or_b32 s60, s3, s0
	v_pk_mul_f32 v[14:15], v[162:163], v[14:15]
	v_pk_mul_f32 v[12:13], v[160:161], v[12:13]
	v_pk_mul_f32 v[166:167], v[154:155], v[166:167]
	v_pk_mul_f32 v[164:165], v[152:153], v[164:165]
	v_pk_mul_f32 v[170:171], v[158:159], v[170:171]
	v_pk_mul_f32 v[168:169], v[156:157], v[168:169]
	ds_write_b128 v80, v[8:11]
	ds_write_b128 v80, v[12:15] offset:64
	ds_write_b128 v80, v[164:167] offset:128
	ds_write_b128 v80, v[168:171] offset:192
	v_lshlrev_b64 v[8:9], 9, v[86:87]
	v_and_b32_e32 v10, 7, v194
	s_lshl_b64 s[36:37], s[60:61], 1
	v_lshl_add_u64 v[8:9], v[8:9], 0, s[8:9]
	v_lshlrev_b32_e32 v80, 4, v10
	s_add_u32 s36, s18, s36
	v_lshl_add_u64 v[8:9], v[8:9], 0, v[80:81]
	s_addc_u32 s37, s19, s37
	s_waitcnt lgkmcnt(0)
	v_lshl_add_u64 v[8:9], s[36:37], 0, v[8:9]
	s_mov_b64 s[36:37], 0x51ff500
	v_lshl_add_u64 v[164:165], v[8:9], 0, s[36:37]
	v_mul_lo_u32 v8, v86, s77
	v_lshlrev_b32_e32 v9, 5, v10
	v_add3_u32 v80, v8, v9, s50
	s_mov_b32 s0, 0

.LBB0_657:
	s_andn2_b64 vcc, exec, s[44:45]
	s_cbranch_vccnz .LBB0_666
	v_mad_u32_u24 v8, v202, s77, v196
	ds_write_b128 v8, v[82:85]
	ds_write_b128 v8, v[160:163] offset:64
	ds_write_b128 v8, v[152:155] offset:128
	ds_write_b128 v8, v[156:159] offset:192
	s_nop 1
	v_readlane_b32 s36, v254, 37
	v_readlane_b32 s37, v254, 38
	s_mov_b64 s[44:45], -1
	s_and_b64 vcc, exec, s[36:37]
	s_cbranch_vccz .LBB0_662
	s_lshl_b64 s[36:37], s[34:35], 17
	s_lshl_b32 s0, s2, 9
	s_add_u32 s36, s0, s36
	v_ashrrev_i32_e32 v173, 31, v172
	s_addc_u32 s37, 0, s37
	s_lshl_b32 s0, s16, 8
	v_readlane_b32 s3, v254, 33
	v_lshlrev_b64 v[8:9], 9, v[172:173]
	s_or_b32 s60, s3, s0
	v_lshl_add_u64 v[8:9], s[36:37], 0, v[8:9]
	v_lshlrev_b32_e32 v10, 4, v194
	s_lshl_b64 s[36:37], s[60:61], 2
	v_and_b32_e32 v10, 0xf0, v10
	s_add_u32 s36, s42, s36
	v_or_b32_e32 v8, v8, v10
	s_addc_u32 s37, s43, s37
	v_lshl_add_u64 v[8:9], s[36:37], 0, v[8:9]
	s_mov_b64 s[36:37], 0x2ffec00
	v_mul_lo_u32 v11, v172, s77
	v_lshl_add_u64 v[8:9], v[8:9], 0, s[36:37]
	v_add3_u32 v10, v11, v10, s97
	s_mov_b32 s0, 0

.LBB0_671:
	v_mad_u32_u24 v80, v202, s77, v196
	ds_write_b128 v80, v[8:11]
	ds_write_b128 v80, v[164:167] offset:64
	ds_write_b128 v80, v[12:15] offset:128
	ds_write_b128 v80, v[168:171] offset:192
	s_nop 1
	v_readlane_b32 s36, v254, 37
	v_readlane_b32 s37, v254, 38
	s_mov_b64 s[44:45], -1
	s_and_b64 vcc, exec, s[36:37]
	s_cbranch_vccz .LBB0_675
	s_lshl_b64 s[36:37], s[34:35], 17
	s_lshl_b32 s0, s2, 9
	v_ashrrev_i32_e32 v173, 31, v172
	s_add_u32 s2, s0, s36
	v_lshlrev_b64 v[8:9], 9, v[172:173]
	s_addc_u32 s3, 0, s37
	v_lshl_add_u64 v[8:9], s[2:3], 0, v[8:9]
	s_lshl_b32 s0, s16, 8
	v_readlane_b32 s2, v254, 33
	s_or_b32 s60, s2, s0
	v_lshlrev_b32_e32 v10, 4, v194
	s_lshl_b64 s[2:3], s[60:61], 2
	v_and_b32_e32 v10, 0xf0, v10
	s_add_u32 s2, s42, s2
	v_or_b32_e32 v8, v8, v10
	s_addc_u32 s3, s43, s3
	v_lshl_add_u64 v[8:9], s[2:3], 0, v[8:9]
	s_mov_b64 s[2:3], 0x27fee00
	v_mul_lo_u32 v11, v172, s77
	v_lshl_add_u64 v[8:9], v[8:9], 0, s[2:3]
	v_add3_u32 v10, v11, v10, s97
	s_mov_b32 s0, 0

.LBB0_684:
	v_mad_u32_u24 v80, v202, s77, v196
	ds_write_b128 v80, v[8:11]
	ds_write_b128 v80, v[164:167] offset:64
	ds_write_b128 v80, v[12:15] offset:128
	ds_write_b128 v80, v[168:171] offset:192
	v_mov_b64_e32 v[8:9], s[28:29]
	s_movk_i32 s0, 0x300
	v_mad_i64_i32 v[8:9], s[2:3], v86, s0, v[8:9]
	s_lshl_b32 s0, s16, 8
	v_readlane_b32 s2, v254, 33
	s_or_b32 s60, s2, s0
	v_and_b32_e32 v10, 7, v194
	s_lshl_b64 s[2:3], s[60:61], 1
	v_lshlrev_b32_e32 v80, 4, v10
	s_add_u32 s2, s18, s2
	v_lshl_add_u64 v[8:9], v[8:9], 0, v[80:81]
	s_addc_u32 s3, s19, s3
	s_waitcnt lgkmcnt(0)
	v_lshl_add_u64 v[8:9], s[2:3], 0, v[8:9]
	s_mov_b64 s[2:3], 0x47ffa00
	v_lshl_add_u64 v[164:165], v[8:9], 0, s[2:3]
	v_mul_lo_u32 v8, v86, s77
	v_lshlrev_b32_e32 v9, 5, v10
	v_add3_u32 v80, v8, v9, s50
	s_mov_b32 s0, 0
	s_mov_b32 s2, 0x3e38aa3b

.LBB0_687:
	s_andn2_b64 vcc, exec, s[44:45]
	s_cbranch_vccnz .LBB0_690
	s_lshl_b32 s0, s16, 8
	v_readlane_b32 s2, v254, 33
	v_mad_u32_u24 v8, v202, s77, v196
	v_ashrrev_i32_e32 v87, 31, v86
	s_or_b32 s60, s2, s0
	ds_write_b128 v8, v[82:85]
	ds_write_b128 v8, v[160:163] offset:64
	ds_write_b128 v8, v[152:155] offset:128
	ds_write_b128 v8, v[156:159] offset:192
	v_lshlrev_b64 v[8:9], 9, v[86:87]
	v_and_b32_e32 v10, 7, v194
	s_lshl_b64 s[2:3], s[60:61], 1
	v_lshl_add_u64 v[8:9], v[8:9], 0, s[8:9]
	v_lshlrev_b32_e32 v80, 4, v10
	s_add_u32 s2, s18, s2
	v_lshl_add_u64 v[8:9], v[8:9], 0, v[80:81]
	s_addc_u32 s3, s19, s3
	s_waitcnt lgkmcnt(0)
	v_lshl_add_u64 v[8:9], s[2:3], 0, v[8:9]
	s_mov_b64 s[2:3], 0x43ffc00
	v_lshl_add_u64 v[164:165], v[8:9], 0, s[2:3]
	v_mul_lo_u32 v8, v86, s77
	v_lshlrev_b32_e32 v9, 5, v10
	v_add3_u32 v80, v8, v9, s50
	s_mov_b32 s0, 0

.LBB0_695:
	s_lshl_b32 s0, s16, 8
	v_readlane_b32 s2, v254, 33
	v_mad_u32_u24 v80, v202, s77, v196
	v_ashrrev_i32_e32 v87, 31, v86
	s_or_b32 s60, s2, s0
	ds_write_b128 v80, v[8:11]
	ds_write_b128 v80, v[12:15] offset:64
	ds_write_b128 v80, v[164:167] offset:128
	ds_write_b128 v80, v[168:171] offset:192
	v_lshlrev_b64 v[8:9], 9, v[86:87]
	v_and_b32_e32 v10, 7, v194
	s_lshl_b64 s[2:3], s[60:61], 1
	v_lshl_add_u64 v[8:9], v[8:9], 0, s[8:9]
	v_lshlrev_b32_e32 v80, 4, v10
	s_add_u32 s2, s18, s2
	v_lshl_add_u64 v[8:9], v[8:9], 0, v[80:81]
	s_addc_u32 s3, s19, s3
	s_waitcnt lgkmcnt(0)
	v_lshl_add_u64 v[8:9], s[2:3], 0, v[8:9]
	s_mov_b64 s[2:3], 0x3fffe00
	v_lshl_add_u64 v[164:165], v[8:9], 0, s[2:3]
	v_mul_lo_u32 v8, v86, s77
	v_lshlrev_b32_e32 v9, 5, v10
	v_add3_u32 v80, v8, v9, s50
	s_mov_b32 s0, 0
	s_mov_b32 s2, 0x3e000000

.LBB0_701:
	s_lshl_b32 s0, s16, 8
	v_readlane_b32 s2, v254, 33
	s_or_b32 s2, s2, s0
	v_mad_u32_u24 v8, v202, s77, v196
	v_ashrrev_i32_e32 v87, 31, v86
	s_ashr_i32 s3, s2, 31
	ds_write_b128 v8, v[82:85]
	ds_write_b128 v8, v[160:163] offset:64
	ds_write_b128 v8, v[152:155] offset:128
	ds_write_b128 v8, v[156:159] offset:192
	v_lshlrev_b64 v[8:9], 9, v[86:87]
	v_and_b32_e32 v10, 7, v194
	s_lshl_b64 s[2:3], s[2:3], 1
	v_lshl_add_u64 v[8:9], v[8:9], 0, s[8:9]
	v_lshlrev_b32_e32 v80, 4, v10
	s_add_u32 s2, s18, s2
	s_waitcnt lgkmcnt(0)
	v_lshl_add_u64 v[8:9], v[8:9], 0, v[80:81]
	s_addc_u32 s3, s19, s3
	v_lshl_add_u64 v[8:9], s[2:3], 0, v[8:9]
	s_mov_b64 s[2:3], 0x3c00000
	v_mul_lo_u32 v11, v86, s77
	v_lshlrev_b32_e32 v10, 5, v10
	v_lshl_add_u64 v[8:9], v[8:9], 0, s[2:3]
	v_add3_u32 v10, v11, v10, s50
	s_mov_b32 s0, 0

.LBB0_716:
	v_mad_u32_u24 v80, v195, s77, v196
	ds_write_b128 v80, v[0:3]
	ds_write_b128 v80, v[4:7] offset:64
	ds_write_b128 v80, v[152:155] offset:128
	ds_write_b128 v80, v[156:159] offset:192
	s_nop 1

.LBB0_718:
	v_mov_b64_e32 v[0:1], v[8:9]
	s_andn2_b64 vcc, exec, s[44:45]
	v_mov_b64_e32 v[2:3], v[10:11]
	v_mov_b64_e32 v[4:5], v[12:13]
	v_mov_b64_e32 v[6:7], v[14:15]
	s_cbranch_vccnz .LBB0_725
	s_cmp_lg_u32 s58, 13
	s_mov_b64 s[44:45], -1
	s_cbranch_scc0 .LBB0_721
	v_mul_f32_e32 v80, 0xbfb8aa3b, v152
	v_exp_f32_e32 v80, v80
	v_mul_f32_e32 v87, 0xbfb8aa3b, v153
	v_exp_f32_e32 v87, v87
	v_mul_f32_e32 v165, 0xbfb8aa3b, v155
	v_add_f32_e32 v80, 1.0, v80
	v_rcp_f32_e32 v164, v80
	v_add_f32_e32 v80, 1.0, v87
	v_mul_f32_e32 v87, 0xbfb8aa3b, v154
	v_exp_f32_e32 v87, v87
	v_exp_f32_e32 v167, v165
	v_rcp_f32_e32 v165, v80
	v_mul_f32_e32 v0, 0xbfb8aa3b, v82
	v_add_f32_e32 v80, 1.0, v87
	v_mul_f32_e32 v87, 0xbfb8aa3b, v156
	v_rcp_f32_e32 v166, v80
	v_add_f32_e32 v80, 1.0, v167
	v_exp_f32_e32 v87, v87
	v_mul_f32_e32 v167, 0xbfb8aa3b, v157
	v_exp_f32_e32 v169, v167
	v_mul_f32_e32 v1, 0xbfb8aa3b, v83
	v_mul_f32_e32 v2, 0xbfb8aa3b, v84
	v_mul_f32_e32 v3, 0xbfb8aa3b, v85
	v_rcp_f32_e32 v167, v80
	v_add_f32_e32 v80, 1.0, v87
	v_mul_f32_e32 v87, 0xbfb8aa3b, v158
	v_exp_f32_e32 v0, v0
	v_exp_f32_e32 v1, v1
	v_exp_f32_e32 v2, v2
	v_exp_f32_e32 v3, v3
	v_mul_f32_e32 v4, 0xbfb8aa3b, v160
	v_mul_f32_e32 v5, 0xbfb8aa3b, v161
	v_mul_f32_e32 v6, 0xbfb8aa3b, v162
	v_mul_f32_e32 v7, 0xbfb8aa3b, v163
	v_rcp_f32_e32 v168, v80
	v_add_f32_e32 v80, 1.0, v169
	v_exp_f32_e32 v87, v87
	v_mul_f32_e32 v169, 0xbfb8aa3b, v159
	v_exp_f32_e32 v4, v4
	v_exp_f32_e32 v5, v5
	v_exp_f32_e32 v6, v6
	v_exp_f32_e32 v7, v7
	v_exp_f32_e32 v171, v169
	v_add_f32_e32 v0, 1.0, v0
	v_add_f32_e32 v1, 1.0, v1
	v_add_f32_e32 v2, 1.0, v2
	v_add_f32_e32 v3, 1.0, v3
	v_rcp_f32_e32 v169, v80
	v_add_f32_e32 v80, 1.0, v87
	v_rcp_f32_e32 v0, v0
	v_rcp_f32_e32 v1, v1
	v_rcp_f32_e32 v2, v2
	v_rcp_f32_e32 v3, v3
	v_add_f32_e32 v4, 1.0, v4
	v_add_f32_e32 v5, 1.0, v5
	v_add_f32_e32 v6, 1.0, v6
	v_add_f32_e32 v7, 1.0, v7
	v_rcp_f32_e32 v170, v80
	v_add_f32_e32 v80, 1.0, v171
	v_rcp_f32_e32 v4, v4
	v_rcp_f32_e32 v5, v5
	v_rcp_f32_e32 v6, v6
	v_rcp_f32_e32 v7, v7
	v_rcp_f32_e32 v171, v80
	v_pk_mul_f32 v[0:1], v[82:83], v[0:1]
	v_pk_mul_f32 v[2:3], v[84:85], v[2:3]
	v_mad_u32_u24 v80, v195, s77, v196
	v_pk_mul_f32 v[4:5], v[160:161], v[4:5]
	v_pk_mul_f32 v[6:7], v[162:163], v[6:7]
	v_pk_mul_f32 v[164:165], v[152:153], v[164:165]
	v_pk_mul_f32 v[166:167], v[154:155], v[166:167]
	v_pk_mul_f32 v[168:169], v[156:157], v[168:169]
	v_pk_mul_f32 v[170:171], v[158:159], v[170:171]
	ds_write_b128 v80, v[0:3]
	ds_write_b128 v80, v[4:7] offset:64
	ds_write_b128 v80, v[164:167] offset:128
	ds_write_b128 v80, v[168:171] offset:192
	s_nop 1
	s_mov_b64 s[44:45], 0

.LBB0_729:
	s_or_b64 exec, exec, s[44:45]
	s_waitcnt lgkmcnt(0)
	ds_read_b128 v[0:3], v201 offset:256
	ds_read_b128 v[4:7], v201 offset:320
	ds_read_b128 v[164:167], v201 offset:384
	ds_read_b128 v[168:171], v201 offset:448
	v_mad_u32_u24 v80, v195, s77, v196
	s_waitcnt lgkmcnt(0)
	v_pk_mul_f32 v[2:3], v[84:85], v[2:3]
	v_pk_mul_f32 v[0:1], v[82:83], v[0:1]
	v_pk_mul_f32 v[6:7], v[162:163], v[6:7]
	v_pk_mul_f32 v[4:5], v[160:161], v[4:5]
	v_pk_mul_f32 v[166:167], v[154:155], v[166:167]
	v_pk_mul_f32 v[164:165], v[152:153], v[164:165]
	v_pk_mul_f32 v[170:171], v[158:159], v[170:171]
	v_pk_mul_f32 v[168:169], v[156:157], v[168:169]
	ds_write_b128 v80, v[0:3]
	ds_write_b128 v80, v[4:7] offset:64
	ds_write_b128 v80, v[164:167] offset:128
	ds_write_b128 v80, v[168:171] offset:192
	s_nop 1
	v_mov_b64_e32 v[0:1], v[8:9]
	v_mov_b64_e32 v[2:3], v[10:11]
	v_mov_b64_e32 v[4:5], v[12:13]
	v_mov_b64_e32 v[6:7], v[14:15]

.LBB0_731:
	s_andn2_b64 vcc, exec, s[44:45]
	s_cbranch_vccnz .LBB0_733
	v_mad_u32_u24 v0, v195, s77, v196
	ds_write_b128 v0, v[82:85]
	ds_write_b128 v0, v[160:163] offset:64
	ds_write_b128 v0, v[152:155] offset:128
	ds_write_b128 v0, v[156:159] offset:192
	s_nop 1
	v_mov_b64_e32 v[0:1], v[8:9]
	v_mov_b64_e32 v[2:3], v[10:11]
	v_mov_b64_e32 v[4:5], v[12:13]
	v_mov_b64_e32 v[6:7], v[14:15]

.LBB0_738:
	v_mad_u32_u24 v80, v195, s77, v196
	ds_write_b128 v80, v[0:3]
	ds_write_b128 v80, v[164:167] offset:64
	ds_write_b128 v80, v[4:7] offset:128
	ds_write_b128 v80, v[168:171] offset:192
	s_nop 1
	v_mov_b64_e32 v[0:1], v[8:9]
	v_mov_b64_e32 v[2:3], v[10:11]
	v_mov_b64_e32 v[4:5], v[12:13]
	v_mov_b64_e32 v[6:7], v[14:15]

.LBB0_753:
	v_mad_u32_u24 v80, v195, s77, v196
	ds_write_b128 v80, v[0:3]
	ds_write_b128 v80, v[4:7] offset:64
	ds_write_b128 v80, v[164:167] offset:128
	ds_write_b128 v80, v[168:171] offset:192
	s_nop 1
	v_mov_b64_e32 v[0:1], v[8:9]
	v_mov_b64_e32 v[2:3], v[10:11]
	v_mov_b64_e32 v[4:5], v[12:13]
	v_mov_b64_e32 v[6:7], v[14:15]

.LBB0_758:
	v_mad_u32_u24 v0, v195, s77, v196
	ds_write_b128 v0, v[82:85]
	ds_write_b128 v0, v[160:163] offset:64
	ds_write_b128 v0, v[152:155] offset:128
	ds_write_b128 v0, v[156:159] offset:192
	s_nop 1
	v_mov_b64_e32 v[0:1], v[8:9]
	v_mov_b64_e32 v[2:3], v[10:11]
	v_mov_b64_e32 v[4:5], v[12:13]
	v_mov_b64_e32 v[6:7], v[14:15]

.LBB0_771:
	v_mad_u32_u24 v80, v202, s77, v196
	ds_write_b128 v80, v[8:11]
	ds_write_b128 v80, v[12:15] offset:64
	ds_write_b128 v80, v[152:155] offset:128
	ds_write_b128 v80, v[156:159] offset:192
	v_readlane_b32 s36, v254, 37
	s_waitcnt lgkmcnt(0)
	v_readlane_b32 s37, v254, 38
	s_andn2_b64 vcc, exec, s[36:37]
	s_cbranch_vccnz .LBB0_774
	s_lshl_b64 s[36:37], s[34:35], 15
	s_lshl_b32 s0, s2, 7
	v_ashrrev_i32_e32 v87, 31, v86
	s_add_u32 s36, s0, s36
	v_lshlrev_b64 v[8:9], 7, v[86:87]
	s_addc_u32 s37, 0, s37
	v_lshlrev_b32_e32 v10, 4, v194
	v_lshl_add_u64 v[8:9], s[36:37], 0, v[8:9]
	v_and_b32_e32 v10, 0x70, v10
	v_or_b32_e32 v8, v8, v10
	v_lshl_add_u64 v[8:9], s[42:43], 0, v[8:9]
	s_mov_b64 s[36:37], 0x4000000
	v_mul_lo_u32 v11, v86, s77
	v_lshl_add_u64 v[8:9], v[8:9], 0, s[36:37]
	v_add3_u32 v10, v11, v10, s97
	s_mov_b32 s0, 0

.LBB0_777:
	v_mov_b64_e32 v[14:15], v[6:7]
	s_andn2_b64 vcc, exec, s[44:45]
	v_mov_b64_e32 v[12:13], v[4:5]
	v_mov_b64_e32 v[10:11], v[2:3]
	v_mov_b64_e32 v[8:9], v[0:1]
	s_cbranch_vccnz .LBB0_786
	s_cmp_lg_u32 s58, 13
	s_mov_b64 s[44:45], -1
	s_cbranch_scc0 .LBB0_782
	v_mul_f32_e32 v80, 0xbfb8aa3b, v152
	v_exp_f32_e32 v80, v80
	v_mul_f32_e32 v87, 0xbfb8aa3b, v153
	v_exp_f32_e32 v87, v87
	v_mul_f32_e32 v165, 0xbfb8aa3b, v155
	v_add_f32_e32 v80, 1.0, v80
	v_rcp_f32_e32 v164, v80
	v_add_f32_e32 v80, 1.0, v87
	v_mul_f32_e32 v87, 0xbfb8aa3b, v154
	v_exp_f32_e32 v87, v87
	v_exp_f32_e32 v167, v165
	v_rcp_f32_e32 v165, v80
	v_mul_f32_e32 v8, 0xbfb8aa3b, v82
	v_add_f32_e32 v80, 1.0, v87
	v_mul_f32_e32 v87, 0xbfb8aa3b, v156
	v_rcp_f32_e32 v166, v80
	v_add_f32_e32 v80, 1.0, v167
	v_exp_f32_e32 v87, v87
	v_mul_f32_e32 v167, 0xbfb8aa3b, v157
	v_exp_f32_e32 v169, v167
	v_mul_f32_e32 v9, 0xbfb8aa3b, v83
	v_mul_f32_e32 v10, 0xbfb8aa3b, v84
	v_mul_f32_e32 v11, 0xbfb8aa3b, v85
	v_rcp_f32_e32 v167, v80
	v_add_f32_e32 v80, 1.0, v87
	v_mul_f32_e32 v87, 0xbfb8aa3b, v158
	v_exp_f32_e32 v8, v8
	v_exp_f32_e32 v9, v9
	v_exp_f32_e32 v10, v10
	v_exp_f32_e32 v11, v11
	v_mul_f32_e32 v12, 0xbfb8aa3b, v160
	v_mul_f32_e32 v13, 0xbfb8aa3b, v161
	v_mul_f32_e32 v14, 0xbfb8aa3b, v162
	v_mul_f32_e32 v15, 0xbfb8aa3b, v163
	v_rcp_f32_e32 v168, v80
	v_add_f32_e32 v80, 1.0, v169
	v_exp_f32_e32 v87, v87
	v_mul_f32_e32 v169, 0xbfb8aa3b, v159
	v_exp_f32_e32 v12, v12
	v_exp_f32_e32 v13, v13
	v_exp_f32_e32 v14, v14
	v_exp_f32_e32 v15, v15
	v_exp_f32_e32 v171, v169
	v_add_f32_e32 v8, 1.0, v8
	v_add_f32_e32 v9, 1.0, v9
	v_add_f32_e32 v10, 1.0, v10
	v_add_f32_e32 v11, 1.0, v11
	v_rcp_f32_e32 v169, v80
	v_add_f32_e32 v80, 1.0, v87
	v_rcp_f32_e32 v8, v8
	v_rcp_f32_e32 v9, v9
	v_rcp_f32_e32 v10, v10
	v_rcp_f32_e32 v11, v11
	v_add_f32_e32 v12, 1.0, v12
	v_add_f32_e32 v13, 1.0, v13
	v_add_f32_e32 v14, 1.0, v14
	v_add_f32_e32 v15, 1.0, v15
	v_rcp_f32_e32 v170, v80
	v_add_f32_e32 v80, 1.0, v171
	v_rcp_f32_e32 v12, v12
	v_rcp_f32_e32 v13, v13
	v_rcp_f32_e32 v14, v14
	v_rcp_f32_e32 v15, v15
	v_rcp_f32_e32 v171, v80
	v_pk_mul_f32 v[8:9], v[82:83], v[8:9]
	v_pk_mul_f32 v[10:11], v[84:85], v[10:11]
	v_mad_u32_u24 v80, v202, s77, v196
	v_ashrrev_i32_e32 v87, 31, v86
	v_readlane_b32 s36, v254, 54
	s_lshl_b32 s0, s16, 8
	v_readlane_b32 s3, v254, 33
	v_pk_mul_f32 v[12:13], v[160:161], v[12:13]
	v_pk_mul_f32 v[14:15], v[162:163], v[14:15]
	v_pk_mul_f32 v[164:165], v[152:153], v[164:165]
	v_pk_mul_f32 v[166:167], v[154:155], v[166:167]
	v_pk_mul_f32 v[168:169], v[156:157], v[168:169]
	v_pk_mul_f32 v[170:171], v[158:159], v[170:171]
	ds_write_b128 v80, v[8:11]
	ds_write_b128 v80, v[12:15] offset:64
	ds_write_b128 v80, v[164:167] offset:128
	ds_write_b128 v80, v[168:171] offset:192
	v_lshlrev_b64 v[8:9], 11, v[86:87]
	v_readlane_b32 s37, v254, 55
	s_or_b32 s60, s3, s0
	v_and_b32_e32 v10, 7, v194
	v_lshl_add_u64 v[8:9], v[8:9], 0, s[36:37]
	s_lshl_b64 s[36:37], s[60:61], 1
	v_lshlrev_b32_e32 v80, 4, v10
	s_add_u32 s36, s18, s36
	s_waitcnt lgkmcnt(0)
	v_lshl_add_u64 v[8:9], v[8:9], 0, v[80:81]
	s_addc_u32 s37, s19, s37
	v_lshl_add_u64 v[8:9], s[36:37], 0, v[8:9]
	s_mov_b64 s[36:37], 0x590f200
	v_mul_lo_u32 v11, v86, s77
	v_lshlrev_b32_e32 v10, 5, v10
	v_lshl_add_u64 v[8:9], v[8:9], 0, s[36:37]
	v_add3_u32 v10, v11, v10, s50
	s_mov_b32 s0, 0
	s_mov_b64 s[36:37], 0x4000

.LBB0_790:
	s_or_b64 exec, exec, s[44:45]
	s_waitcnt lgkmcnt(0)
	ds_read_b128 v[8:11], v201 offset:256
	ds_read_b128 v[12:15], v201 offset:320
	ds_read_b128 v[164:167], v201 offset:384
	ds_read_b128 v[168:171], v201 offset:448
	s_lshl_b32 s0, s16, 8
	v_readlane_b32 s3, v254, 33
	s_waitcnt lgkmcnt(0)
	v_pk_mul_f32 v[10:11], v[84:85], v[10:11]
	v_pk_mul_f32 v[8:9], v[82:83], v[8:9]
	v_mad_u32_u24 v80, v202, s77, v196
	v_ashrrev_i32_e32 v87, 31, v86
	s_or_b32 s60, s3, s0
	v_pk_mul_f32 v[14:15], v[162:163], v[14:15]
	v_pk_mul_f32 v[12:13], v[160:161], v[12:13]
	v_pk_mul_f32 v[166:167], v[154:155], v[166:167]
	v_pk_mul_f32 v[164:165], v[152:153], v[164:165]
	v_pk_mul_f32 v[170:171], v[158:159], v[170:171]
	v_pk_mul_f32 v[168:169], v[156:157], v[168:169]
	ds_write_b128 v80, v[8:11]
	ds_write_b128 v80, v[12:15] offset:64
	ds_write_b128 v80, v[164:167] offset:128
	ds_write_b128 v80, v[168:171] offset:192
	v_lshlrev_b64 v[8:9], 9, v[86:87]
	v_and_b32_e32 v10, 7, v194
	s_lshl_b64 s[36:37], s[60:61], 1
	v_lshl_add_u64 v[8:9], v[8:9], 0, s[8:9]
	v_lshlrev_b32_e32 v80, 4, v10
	s_add_u32 s36, s18, s36
	v_lshl_add_u64 v[8:9], v[8:9], 0, v[80:81]
	s_addc_u32 s37, s19, s37
	s_waitcnt lgkmcnt(0)
	v_lshl_add_u64 v[8:9], s[36:37], 0, v[8:9]
	s_mov_b64 s[36:37], 0x5203500
	v_lshl_add_u64 v[164:165], v[8:9], 0, s[36:37]
	v_mul_lo_u32 v8, v86, s77
	v_lshlrev_b32_e32 v9, 5, v10
	v_add3_u32 v80, v8, v9, s50
	s_mov_b32 s0, 0

.LBB0_820:
	v_mad_u32_u24 v80, v202, s77, v196
	ds_write_b128 v80, v[8:11]
	ds_write_b128 v80, v[164:167] offset:64
	ds_write_b128 v80, v[12:15] offset:128
	ds_write_b128 v80, v[168:171] offset:192
	v_mov_b64_e32 v[8:9], s[28:29]
	s_movk_i32 s0, 0x300
	v_mad_i64_i32 v[8:9], s[2:3], v86, s0, v[8:9]
	s_lshl_b32 s0, s16, 8
	v_readlane_b32 s2, v254, 33
	s_or_b32 s60, s2, s0
	v_and_b32_e32 v10, 7, v194
	s_lshl_b64 s[2:3], s[60:61], 1
	v_lshlrev_b32_e32 v80, 4, v10
	s_add_u32 s2, s18, s2
	v_lshl_add_u64 v[8:9], v[8:9], 0, v[80:81]
	s_addc_u32 s3, s19, s3
	s_waitcnt lgkmcnt(0)
	v_lshl_add_u64 v[8:9], s[2:3], 0, v[8:9]
	s_mov_b64 s[2:3], 0x4805a00
	v_lshl_add_u64 v[164:165], v[8:9], 0, s[2:3]
	v_mul_lo_u32 v8, v86, s77
	v_lshlrev_b32_e32 v9, 5, v10
	v_add3_u32 v80, v8, v9, s50
	s_mov_b32 s0, 0
	s_mov_b32 s2, 0x3e38aa3b

.LBB0_823:
	s_andn2_b64 vcc, exec, s[44:45]
	s_cbranch_vccnz .LBB0_826
	s_lshl_b32 s0, s16, 8
	v_readlane_b32 s2, v254, 33
	v_mad_u32_u24 v8, v202, s77, v196
	v_ashrrev_i32_e32 v87, 31, v86
	s_or_b32 s60, s2, s0
	ds_write_b128 v8, v[82:85]
	ds_write_b128 v8, v[160:163] offset:64
	ds_write_b128 v8, v[152:155] offset:128
	ds_write_b128 v8, v[156:159] offset:192
	v_lshlrev_b64 v[8:9], 9, v[86:87]
	v_and_b32_e32 v10, 7, v194
	s_lshl_b64 s[2:3], s[60:61], 1
	v_lshl_add_u64 v[8:9], v[8:9], 0, s[8:9]
	v_lshlrev_b32_e32 v80, 4, v10
	s_add_u32 s2, s18, s2
	v_lshl_add_u64 v[8:9], v[8:9], 0, v[80:81]
	s_addc_u32 s3, s19, s3
	s_waitcnt lgkmcnt(0)
	v_lshl_add_u64 v[8:9], s[2:3], 0, v[8:9]
	s_mov_b64 s[2:3], 0x4403c00
	v_lshl_add_u64 v[164:165], v[8:9], 0, s[2:3]
	v_mul_lo_u32 v8, v86, s77
	v_lshlrev_b32_e32 v9, 5, v10
	v_add3_u32 v80, v8, v9, s50
	s_mov_b32 s0, 0

.LBB0_831:
	s_lshl_b32 s0, s16, 8
	v_readlane_b32 s2, v254, 33
	v_mad_u32_u24 v80, v202, s77, v196
	v_ashrrev_i32_e32 v87, 31, v86
	s_or_b32 s60, s2, s0
	ds_write_b128 v80, v[8:11]
	ds_write_b128 v80, v[12:15] offset:64
	ds_write_b128 v80, v[164:167] offset:128
	ds_write_b128 v80, v[168:171] offset:192
	v_lshlrev_b64 v[8:9], 9, v[86:87]
	v_and_b32_e32 v10, 7, v194
	s_lshl_b64 s[2:3], s[60:61], 1
	v_lshl_add_u64 v[8:9], v[8:9], 0, s[8:9]
	v_lshlrev_b32_e32 v80, 4, v10
	s_add_u32 s2, s18, s2
	v_lshl_add_u64 v[8:9], v[8:9], 0, v[80:81]
	s_addc_u32 s3, s19, s3
	s_waitcnt lgkmcnt(0)
	v_lshl_add_u64 v[8:9], s[2:3], 0, v[8:9]
	s_mov_b64 s[2:3], 0x4003e00
	v_lshl_add_u64 v[164:165], v[8:9], 0, s[2:3]
	v_mul_lo_u32 v8, v86, s77
	v_lshlrev_b32_e32 v9, 5, v10
	v_add3_u32 v80, v8, v9, s50
	s_mov_b32 s0, 0
	s_mov_b32 s2, 0x3e000000

.LBB0_837:
	s_lshl_b32 s0, s16, 8
	v_readlane_b32 s2, v254, 33
	s_or_b32 s2, s2, s0
	v_mad_u32_u24 v8, v202, s77, v196
	v_ashrrev_i32_e32 v87, 31, v86
	s_ashr_i32 s3, s2, 31
	ds_write_b128 v8, v[82:85]
	ds_write_b128 v8, v[160:163] offset:64
	ds_write_b128 v8, v[152:155] offset:128
	ds_write_b128 v8, v[156:159] offset:192
	v_lshlrev_b64 v[8:9], 9, v[86:87]
	v_and_b32_e32 v10, 7, v194
	s_lshl_b64 s[2:3], s[2:3], 1
	v_lshl_add_u64 v[8:9], v[8:9], 0, s[8:9]
	v_lshlrev_b32_e32 v80, 4, v10
	s_add_u32 s2, s18, s2
	s_waitcnt lgkmcnt(0)
	v_lshl_add_u64 v[8:9], v[8:9], 0, v[80:81]
	s_addc_u32 s3, s19, s3
	v_lshl_add_u64 v[8:9], s[2:3], 0, v[8:9]
	s_mov_b64 s[2:3], 0x3c04000
	v_mul_lo_u32 v11, v86, s77
	v_lshlrev_b32_e32 v10, 5, v10
	v_lshl_add_u64 v[8:9], v[8:9], 0, s[2:3]
	v_add3_u32 v10, v11, v10, s50
	s_mov_b32 s0, 0

.LBB0_913:
	v_mov_b64_e32 v[14:15], v[6:7]
	s_andn2_b64 vcc, exec, s[44:45]
	v_mov_b64_e32 v[12:13], v[4:5]
	v_mov_b64_e32 v[10:11], v[2:3]
	v_mov_b64_e32 v[8:9], v[0:1]
	s_cbranch_vccnz .LBB0_922
	s_cmp_lg_u32 s58, 13
	s_mov_b64 s[44:45], -1
	s_cbranch_scc0 .LBB0_918
	v_mul_f32_e32 v80, 0xbfb8aa3b, v152
	v_exp_f32_e32 v80, v80
	v_mul_f32_e32 v87, 0xbfb8aa3b, v153
	v_exp_f32_e32 v87, v87
	v_mul_f32_e32 v165, 0xbfb8aa3b, v155
	v_add_f32_e32 v80, 1.0, v80
	v_rcp_f32_e32 v164, v80
	v_add_f32_e32 v80, 1.0, v87
	v_mul_f32_e32 v87, 0xbfb8aa3b, v154
	v_exp_f32_e32 v87, v87
	v_exp_f32_e32 v167, v165
	v_rcp_f32_e32 v165, v80
	v_mul_f32_e32 v8, 0xbfb8aa3b, v82
	v_add_f32_e32 v80, 1.0, v87
	v_mul_f32_e32 v87, 0xbfb8aa3b, v156
	v_rcp_f32_e32 v166, v80
	v_add_f32_e32 v80, 1.0, v167
	v_exp_f32_e32 v87, v87
	v_mul_f32_e32 v167, 0xbfb8aa3b, v157
	v_exp_f32_e32 v169, v167
	v_mul_f32_e32 v9, 0xbfb8aa3b, v83
	v_mul_f32_e32 v10, 0xbfb8aa3b, v84
	v_mul_f32_e32 v11, 0xbfb8aa3b, v85
	v_rcp_f32_e32 v167, v80
	v_add_f32_e32 v80, 1.0, v87
	v_mul_f32_e32 v87, 0xbfb8aa3b, v158
	v_exp_f32_e32 v8, v8
	v_exp_f32_e32 v9, v9
	v_exp_f32_e32 v10, v10
	v_exp_f32_e32 v11, v11
	v_mul_f32_e32 v12, 0xbfb8aa3b, v160
	v_mul_f32_e32 v13, 0xbfb8aa3b, v161
	v_mul_f32_e32 v14, 0xbfb8aa3b, v162
	v_mul_f32_e32 v15, 0xbfb8aa3b, v163
	v_rcp_f32_e32 v168, v80
	v_add_f32_e32 v80, 1.0, v169
	v_exp_f32_e32 v87, v87
	v_mul_f32_e32 v169, 0xbfb8aa3b, v159
	v_exp_f32_e32 v12, v12
	v_exp_f32_e32 v13, v13
	v_exp_f32_e32 v14, v14
	v_exp_f32_e32 v15, v15
	v_exp_f32_e32 v171, v169
	v_add_f32_e32 v8, 1.0, v8
	v_add_f32_e32 v9, 1.0, v9
	v_add_f32_e32 v10, 1.0, v10
	v_add_f32_e32 v11, 1.0, v11
	v_rcp_f32_e32 v169, v80
	v_add_f32_e32 v80, 1.0, v87
	v_rcp_f32_e32 v8, v8
	v_rcp_f32_e32 v9, v9
	v_rcp_f32_e32 v10, v10
	v_rcp_f32_e32 v11, v11
	v_add_f32_e32 v12, 1.0, v12
	v_add_f32_e32 v13, 1.0, v13
	v_add_f32_e32 v14, 1.0, v14
	v_add_f32_e32 v15, 1.0, v15
	v_rcp_f32_e32 v170, v80
	v_add_f32_e32 v80, 1.0, v171
	v_rcp_f32_e32 v12, v12
	v_rcp_f32_e32 v13, v13
	v_rcp_f32_e32 v14, v14
	v_rcp_f32_e32 v15, v15
	v_rcp_f32_e32 v171, v80
	v_pk_mul_f32 v[8:9], v[82:83], v[8:9]
	v_pk_mul_f32 v[10:11], v[84:85], v[10:11]
	v_mad_u32_u24 v80, v202, s77, v196
	v_ashrrev_i32_e32 v87, 31, v86
	v_readlane_b32 s36, v254, 54
	s_lshl_b32 s0, s16, 8
	v_readlane_b32 s3, v254, 33
	v_pk_mul_f32 v[12:13], v[160:161], v[12:13]
	v_pk_mul_f32 v[14:15], v[162:163], v[14:15]
	v_pk_mul_f32 v[164:165], v[152:153], v[164:165]
	v_pk_mul_f32 v[166:167], v[154:155], v[166:167]
	v_pk_mul_f32 v[168:169], v[156:157], v[168:169]
	v_pk_mul_f32 v[170:171], v[158:159], v[170:171]
	ds_write_b128 v80, v[8:11]
	ds_write_b128 v80, v[12:15] offset:64
	ds_write_b128 v80, v[164:167] offset:128
	ds_write_b128 v80, v[168:171] offset:192
	v_lshlrev_b64 v[8:9], 11, v[86:87]
	v_readlane_b32 s37, v254, 55
	s_or_b32 s60, s3, s0
	v_and_b32_e32 v10, 7, v194
	v_lshl_add_u64 v[8:9], v[8:9], 0, s[36:37]
	s_lshl_b64 s[36:37], s[60:61], 1
	v_lshlrev_b32_e32 v80, 4, v10
	s_add_u32 s36, s18, s36
	s_waitcnt lgkmcnt(0)
	v_lshl_add_u64 v[8:9], v[8:9], 0, v[80:81]
	s_addc_u32 s37, s19, s37
	v_lshl_add_u64 v[8:9], s[36:37], 0, v[8:9]
	s_mov_b64 s[36:37], 0x591f200
	v_mul_lo_u32 v11, v86, s77
	v_lshlrev_b32_e32 v10, 5, v10
	v_lshl_add_u64 v[8:9], v[8:9], 0, s[36:37]
	v_add3_u32 v10, v11, v10, s50
	s_mov_b32 s0, 0
	s_mov_b64 s[36:37], 0x4000

.LBB0_926:
	s_or_b64 exec, exec, s[44:45]
	s_waitcnt lgkmcnt(0)
	ds_read_b128 v[8:11], v201 offset:256
	ds_read_b128 v[12:15], v201 offset:320
	ds_read_b128 v[164:167], v201 offset:384
	ds_read_b128 v[168:171], v201 offset:448
	s_lshl_b32 s0, s16, 8
	v_readlane_b32 s3, v254, 33
	s_waitcnt lgkmcnt(0)
	v_pk_mul_f32 v[10:11], v[84:85], v[10:11]
	v_pk_mul_f32 v[8:9], v[82:83], v[8:9]
	v_mad_u32_u24 v80, v202, s77, v196
	v_ashrrev_i32_e32 v87, 31, v86
	s_or_b32 s60, s3, s0
	v_pk_mul_f32 v[14:15], v[162:163], v[14:15]
	v_pk_mul_f32 v[12:13], v[160:161], v[12:13]
	v_pk_mul_f32 v[166:167], v[154:155], v[166:167]
	v_pk_mul_f32 v[164:165], v[152:153], v[164:165]
	v_pk_mul_f32 v[170:171], v[158:159], v[170:171]
	v_pk_mul_f32 v[168:169], v[156:157], v[168:169]
	ds_write_b128 v80, v[8:11]
	ds_write_b128 v80, v[12:15] offset:64
	ds_write_b128 v80, v[164:167] offset:128
	ds_write_b128 v80, v[168:171] offset:192
	v_lshlrev_b64 v[8:9], 9, v[86:87]
	v_and_b32_e32 v10, 7, v194
	s_lshl_b64 s[36:37], s[60:61], 1
	v_lshl_add_u64 v[8:9], v[8:9], 0, s[8:9]
	v_lshlrev_b32_e32 v80, 4, v10
	s_add_u32 s36, s18, s36
	v_lshl_add_u64 v[8:9], v[8:9], 0, v[80:81]
	s_addc_u32 s37, s19, s37
	s_waitcnt lgkmcnt(0)
	v_lshl_add_u64 v[8:9], s[36:37], 0, v[8:9]
	s_mov_b64 s[36:37], 0x5207500
	v_lshl_add_u64 v[164:165], v[8:9], 0, s[36:37]
	v_mul_lo_u32 v8, v86, s77
	v_lshlrev_b32_e32 v9, 5, v10
	v_add3_u32 v80, v8, v9, s50
	s_mov_b32 s0, 0

.LBB0_956:
	v_mad_u32_u24 v80, v202, s77, v196
	ds_write_b128 v80, v[8:11]
	ds_write_b128 v80, v[164:167] offset:64
	ds_write_b128 v80, v[12:15] offset:128
	ds_write_b128 v80, v[168:171] offset:192
	v_mov_b64_e32 v[8:9], s[28:29]
	s_movk_i32 s0, 0x300
	v_mad_i64_i32 v[8:9], s[2:3], v86, s0, v[8:9]
	s_lshl_b32 s0, s16, 8
	v_readlane_b32 s2, v254, 33
	s_or_b32 s60, s2, s0
	v_and_b32_e32 v10, 7, v194
	s_lshl_b64 s[2:3], s[60:61], 1
	v_lshlrev_b32_e32 v80, 4, v10
	s_add_u32 s2, s18, s2
	v_lshl_add_u64 v[8:9], v[8:9], 0, v[80:81]
	s_addc_u32 s3, s19, s3
	s_waitcnt lgkmcnt(0)
	v_lshl_add_u64 v[8:9], s[2:3], 0, v[8:9]
	s_mov_b64 s[2:3], 0x480ba00
	v_lshl_add_u64 v[164:165], v[8:9], 0, s[2:3]
	v_mul_lo_u32 v8, v86, s77
	v_lshlrev_b32_e32 v9, 5, v10
	v_add3_u32 v80, v8, v9, s50
	s_mov_b32 s0, 0
	s_mov_b32 s2, 0x3e38aa3b

.LBB0_959:
	s_andn2_b64 vcc, exec, s[44:45]
	s_cbranch_vccnz .LBB0_962
	s_lshl_b32 s0, s16, 8
	v_readlane_b32 s2, v254, 33
	v_mad_u32_u24 v8, v202, s77, v196
	v_ashrrev_i32_e32 v87, 31, v86
	s_or_b32 s60, s2, s0
	ds_write_b128 v8, v[82:85]
	ds_write_b128 v8, v[160:163] offset:64
	ds_write_b128 v8, v[152:155] offset:128
	ds_write_b128 v8, v[156:159] offset:192
	v_lshlrev_b64 v[8:9], 9, v[86:87]
	v_and_b32_e32 v10, 7, v194
	s_lshl_b64 s[2:3], s[60:61], 1
	v_lshl_add_u64 v[8:9], v[8:9], 0, s[8:9]
	v_lshlrev_b32_e32 v80, 4, v10
	s_add_u32 s2, s18, s2
	v_lshl_add_u64 v[8:9], v[8:9], 0, v[80:81]
	s_addc_u32 s3, s19, s3
	s_waitcnt lgkmcnt(0)
	v_lshl_add_u64 v[8:9], s[2:3], 0, v[8:9]
	s_mov_b64 s[2:3], 0x4407c00
	v_lshl_add_u64 v[164:165], v[8:9], 0, s[2:3]
	v_mul_lo_u32 v8, v86, s77
	v_lshlrev_b32_e32 v9, 5, v10
	v_add3_u32 v80, v8, v9, s50
	s_mov_b32 s0, 0

.LBB0_967:
	s_lshl_b32 s0, s16, 8
	v_readlane_b32 s2, v254, 33
	v_mad_u32_u24 v80, v202, s77, v196
	v_ashrrev_i32_e32 v87, 31, v86
	s_or_b32 s60, s2, s0
	ds_write_b128 v80, v[8:11]
	ds_write_b128 v80, v[12:15] offset:64
	ds_write_b128 v80, v[164:167] offset:128
	ds_write_b128 v80, v[168:171] offset:192
	v_lshlrev_b64 v[8:9], 9, v[86:87]
	v_and_b32_e32 v10, 7, v194
	s_lshl_b64 s[2:3], s[60:61], 1
	v_lshl_add_u64 v[8:9], v[8:9], 0, s[8:9]
	v_lshlrev_b32_e32 v80, 4, v10
	s_add_u32 s2, s18, s2
	v_lshl_add_u64 v[8:9], v[8:9], 0, v[80:81]
	s_addc_u32 s3, s19, s3
	s_waitcnt lgkmcnt(0)
	v_lshl_add_u64 v[8:9], s[2:3], 0, v[8:9]
	s_mov_b64 s[2:3], 0x4007e00
	v_lshl_add_u64 v[164:165], v[8:9], 0, s[2:3]
	v_mul_lo_u32 v8, v86, s77
	v_lshlrev_b32_e32 v9, 5, v10
	v_add3_u32 v80, v8, v9, s50
	s_mov_b32 s0, 0
	s_mov_b32 s2, 0x3e000000

.LBB0_973:
	s_lshl_b32 s0, s16, 8
	v_readlane_b32 s2, v254, 33
	s_or_b32 s2, s2, s0
	v_mad_u32_u24 v8, v202, s77, v196
	v_ashrrev_i32_e32 v87, 31, v86
	s_ashr_i32 s3, s2, 31
	ds_write_b128 v8, v[82:85]
	ds_write_b128 v8, v[160:163] offset:64
	ds_write_b128 v8, v[152:155] offset:128
	ds_write_b128 v8, v[156:159] offset:192
	v_lshlrev_b64 v[8:9], 9, v[86:87]
	v_and_b32_e32 v10, 7, v194
	s_lshl_b64 s[2:3], s[2:3], 1
	v_lshl_add_u64 v[8:9], v[8:9], 0, s[8:9]
	v_lshlrev_b32_e32 v80, 4, v10
	s_add_u32 s2, s18, s2
	s_waitcnt lgkmcnt(0)
	v_lshl_add_u64 v[8:9], v[8:9], 0, v[80:81]
	s_addc_u32 s3, s19, s3
	v_lshl_add_u64 v[8:9], s[2:3], 0, v[8:9]
	s_mov_b64 s[2:3], 0x3c08000
	v_mul_lo_u32 v11, v86, s77
	v_lshlrev_b32_e32 v10, 5, v10
	v_lshl_add_u64 v[8:9], v[8:9], 0, s[2:3]
	v_add3_u32 v10, v11, v10, s50
	s_mov_b32 s0, 0

.LBB0_1043:
	v_mad_u32_u24 v80, v202, s77, v196
	ds_write_b128 v80, v[8:11]
	ds_write_b128 v80, v[12:15] offset:64
	ds_write_b128 v80, v[152:155] offset:128
	ds_write_b128 v80, v[156:159] offset:192
	v_readlane_b32 s26, v254, 37
	s_waitcnt lgkmcnt(0)
	v_readlane_b32 s27, v254, 38
	s_mov_b32 s3, s57
	s_andn2_b64 vcc, exec, s[26:27]
	s_cbranch_vccnz .LBB0_1046
	s_lshl_b64 s[26:27], s[34:35], 15
	s_lshl_b32 s0, s2, 7
	v_ashrrev_i32_e32 v87, 31, v86
	s_add_u32 s26, s0, s26
	v_lshlrev_b64 v[8:9], 7, v[86:87]
	s_addc_u32 s27, 0, s27
	v_lshlrev_b32_e32 v10, 4, v194
	v_lshl_add_u64 v[8:9], s[26:27], 0, v[8:9]
	v_and_b32_e32 v10, 0x70, v10
	v_or_b32_e32 v8, v8, v10
	v_lshl_add_u64 v[8:9], s[42:43], 0, v[8:9]
	s_mov_b64 s[26:27], 0x4000000
	v_mul_lo_u32 v11, v86, s77
	v_lshl_add_u64 v[8:9], v[8:9], 0, s[26:27]
	v_add3_u32 v10, v11, v10, s97
	s_mov_b32 s0, 0

.LBB0_1049:
	v_mov_b64_e32 v[14:15], v[6:7]
	s_andn2_b64 vcc, exec, s[44:45]
	v_mov_b64_e32 v[12:13], v[4:5]
	v_mov_b64_e32 v[10:11], v[2:3]
	v_mov_b64_e32 v[8:9], v[0:1]
	s_cbranch_vccnz .LBB0_1058
	s_cmp_lg_u32 s58, 13
	s_mov_b64 s[44:45], -1
	s_cbranch_scc0 .LBB0_1054
	v_mul_f32_e32 v80, 0xbfb8aa3b, v152
	v_exp_f32_e32 v80, v80
	v_mul_f32_e32 v87, 0xbfb8aa3b, v153
	v_exp_f32_e32 v87, v87
	v_mul_f32_e32 v165, 0xbfb8aa3b, v155
	v_add_f32_e32 v80, 1.0, v80
	v_rcp_f32_e32 v164, v80
	v_add_f32_e32 v80, 1.0, v87
	v_mul_f32_e32 v87, 0xbfb8aa3b, v154
	v_exp_f32_e32 v87, v87
	v_exp_f32_e32 v167, v165
	v_rcp_f32_e32 v165, v80
	v_mul_f32_e32 v8, 0xbfb8aa3b, v82
	v_add_f32_e32 v80, 1.0, v87
	v_mul_f32_e32 v87, 0xbfb8aa3b, v156
	v_rcp_f32_e32 v166, v80
	v_add_f32_e32 v80, 1.0, v167
	v_exp_f32_e32 v87, v87
	v_mul_f32_e32 v167, 0xbfb8aa3b, v157
	v_exp_f32_e32 v169, v167
	v_mul_f32_e32 v9, 0xbfb8aa3b, v83
	v_mul_f32_e32 v10, 0xbfb8aa3b, v84
	v_mul_f32_e32 v11, 0xbfb8aa3b, v85
	v_rcp_f32_e32 v167, v80
	v_add_f32_e32 v80, 1.0, v87
	v_mul_f32_e32 v87, 0xbfb8aa3b, v158
	v_exp_f32_e32 v8, v8
	v_exp_f32_e32 v9, v9
	v_exp_f32_e32 v10, v10
	v_exp_f32_e32 v11, v11
	v_mul_f32_e32 v12, 0xbfb8aa3b, v160
	v_mul_f32_e32 v13, 0xbfb8aa3b, v161
	v_mul_f32_e32 v14, 0xbfb8aa3b, v162
	v_mul_f32_e32 v15, 0xbfb8aa3b, v163
	v_rcp_f32_e32 v168, v80
	v_add_f32_e32 v80, 1.0, v169
	v_exp_f32_e32 v87, v87
	v_mul_f32_e32 v169, 0xbfb8aa3b, v159
	v_exp_f32_e32 v12, v12
	v_exp_f32_e32 v13, v13
	v_exp_f32_e32 v14, v14
	v_exp_f32_e32 v15, v15
	v_exp_f32_e32 v171, v169
	v_add_f32_e32 v8, 1.0, v8
	v_add_f32_e32 v9, 1.0, v9
	v_add_f32_e32 v10, 1.0, v10
	v_add_f32_e32 v11, 1.0, v11
	v_rcp_f32_e32 v169, v80
	v_add_f32_e32 v80, 1.0, v87
	v_rcp_f32_e32 v8, v8
	v_rcp_f32_e32 v9, v9
	v_rcp_f32_e32 v10, v10
	v_rcp_f32_e32 v11, v11
	v_add_f32_e32 v12, 1.0, v12
	v_add_f32_e32 v13, 1.0, v13
	v_add_f32_e32 v14, 1.0, v14
	v_add_f32_e32 v15, 1.0, v15
	v_rcp_f32_e32 v170, v80
	v_add_f32_e32 v80, 1.0, v171
	v_rcp_f32_e32 v12, v12
	v_rcp_f32_e32 v13, v13
	v_rcp_f32_e32 v14, v14
	v_rcp_f32_e32 v15, v15
	v_rcp_f32_e32 v171, v80
	v_pk_mul_f32 v[8:9], v[82:83], v[8:9]
	v_pk_mul_f32 v[10:11], v[84:85], v[10:11]
	v_mad_u32_u24 v80, v202, s77, v196
	v_ashrrev_i32_e32 v87, 31, v86
	v_readlane_b32 s26, v254, 54
	s_lshl_b32 s0, s16, 8
	v_readlane_b32 s3, v254, 33
	v_pk_mul_f32 v[12:13], v[160:161], v[12:13]
	v_pk_mul_f32 v[14:15], v[162:163], v[14:15]
	v_pk_mul_f32 v[164:165], v[152:153], v[164:165]
	v_pk_mul_f32 v[166:167], v[154:155], v[166:167]
	v_pk_mul_f32 v[168:169], v[156:157], v[168:169]
	v_pk_mul_f32 v[170:171], v[158:159], v[170:171]
	ds_write_b128 v80, v[8:11]
	ds_write_b128 v80, v[12:15] offset:64
	ds_write_b128 v80, v[164:167] offset:128
	ds_write_b128 v80, v[168:171] offset:192
	v_lshlrev_b64 v[8:9], 11, v[86:87]
	v_readlane_b32 s27, v254, 55
	s_or_b32 s60, s3, s0
	v_and_b32_e32 v10, 7, v194
	v_lshl_add_u64 v[8:9], v[8:9], 0, s[26:27]
	s_lshl_b64 s[26:27], s[60:61], 1
	v_lshlrev_b32_e32 v80, 4, v10
	s_add_u32 s26, s18, s26
	s_waitcnt lgkmcnt(0)
	v_lshl_add_u64 v[8:9], v[8:9], 0, v[80:81]
	s_addc_u32 s27, s19, s27
	v_lshl_add_u64 v[8:9], s[26:27], 0, v[8:9]
	s_mov_b64 s[26:27], 0x592f200
	v_mul_lo_u32 v11, v86, s77
	v_lshlrev_b32_e32 v10, 5, v10
	v_lshl_add_u64 v[8:9], v[8:9], 0, s[26:27]
	v_add3_u32 v10, v11, v10, s50
	s_mov_b32 s0, 0
	s_mov_b64 s[26:27], 0x4000

.LBB0_1062:
	s_or_b64 exec, exec, s[44:45]
	s_waitcnt lgkmcnt(0)
	ds_read_b128 v[8:11], v201 offset:256
	ds_read_b128 v[12:15], v201 offset:320
	ds_read_b128 v[164:167], v201 offset:384
	ds_read_b128 v[168:171], v201 offset:448
	s_lshl_b32 s0, s16, 8
	v_readlane_b32 s3, v254, 33
	s_waitcnt lgkmcnt(0)
	v_pk_mul_f32 v[10:11], v[84:85], v[10:11]
	v_pk_mul_f32 v[8:9], v[82:83], v[8:9]
	v_mad_u32_u24 v80, v202, s77, v196
	v_ashrrev_i32_e32 v87, 31, v86
	s_or_b32 s60, s3, s0
	v_pk_mul_f32 v[14:15], v[162:163], v[14:15]
	v_pk_mul_f32 v[12:13], v[160:161], v[12:13]
	v_pk_mul_f32 v[166:167], v[154:155], v[166:167]
	v_pk_mul_f32 v[164:165], v[152:153], v[164:165]
	v_pk_mul_f32 v[170:171], v[158:159], v[170:171]
	v_pk_mul_f32 v[168:169], v[156:157], v[168:169]
	ds_write_b128 v80, v[8:11]
	ds_write_b128 v80, v[12:15] offset:64
	ds_write_b128 v80, v[164:167] offset:128
	ds_write_b128 v80, v[168:171] offset:192
	v_lshlrev_b64 v[8:9], 9, v[86:87]
	v_and_b32_e32 v10, 7, v194
	s_lshl_b64 s[26:27], s[60:61], 1
	v_lshl_add_u64 v[8:9], v[8:9], 0, s[8:9]
	v_lshlrev_b32_e32 v80, 4, v10
	s_add_u32 s26, s18, s26
	v_lshl_add_u64 v[8:9], v[8:9], 0, v[80:81]
	s_addc_u32 s27, s19, s27
	s_waitcnt lgkmcnt(0)
	v_lshl_add_u64 v[8:9], s[26:27], 0, v[8:9]
	s_mov_b64 s[26:27], 0x520b500
	v_lshl_add_u64 v[164:165], v[8:9], 0, s[26:27]
	v_mul_lo_u32 v8, v86, s77
	v_lshlrev_b32_e32 v9, 5, v10
	v_add3_u32 v80, v8, v9, s50
	s_mov_b32 s0, 0

.LBB0_1065:
	s_andn2_b64 vcc, exec, s[44:45]
	s_cbranch_vccnz .LBB0_1074
	v_mad_u32_u24 v8, v202, s77, v196
	ds_write_b128 v8, v[82:85]
	ds_write_b128 v8, v[160:163] offset:64
	ds_write_b128 v8, v[152:155] offset:128
	ds_write_b128 v8, v[156:159] offset:192
	s_nop 1
	v_readlane_b32 s36, v254, 37
	v_readlane_b32 s37, v254, 38
	s_mov_b64 s[26:27], -1
	s_and_b64 vcc, exec, s[36:37]
	s_cbranch_vccz .LBB0_1070
	s_lshl_b64 s[26:27], s[34:35], 17
	s_lshl_b32 s0, s2, 9
	s_add_u32 s26, s0, s26
	v_ashrrev_i32_e32 v173, 31, v172
	s_addc_u32 s27, 0, s27
	s_lshl_b32 s0, s16, 8
	v_readlane_b32 s3, v254, 33
	v_lshlrev_b64 v[8:9], 9, v[172:173]
	s_or_b32 s60, s3, s0
	v_lshl_add_u64 v[8:9], s[26:27], 0, v[8:9]
	v_lshlrev_b32_e32 v10, 4, v194
	s_lshl_b64 s[26:27], s[60:61], 2
	v_and_b32_e32 v10, 0xf0, v10
	s_add_u32 s26, s42, s26
	v_or_b32_e32 v8, v8, v10
	s_addc_u32 s27, s43, s27
	v_lshl_add_u64 v[8:9], s[26:27], 0, v[8:9]
	s_mov_b64 s[26:27], 0x2ffec00
	v_mul_lo_u32 v11, v172, s77
	v_lshl_add_u64 v[8:9], v[8:9], 0, s[26:27]
	v_add3_u32 v10, v11, v10, s97
	s_mov_b32 s0, 0

.LBB0_1079:
	v_mad_u32_u24 v80, v202, s77, v196
	ds_write_b128 v80, v[8:11]
	ds_write_b128 v80, v[164:167] offset:64
	ds_write_b128 v80, v[12:15] offset:128
	ds_write_b128 v80, v[168:171] offset:192
	s_nop 1
	v_readlane_b32 s36, v254, 37
	v_readlane_b32 s37, v254, 38
	s_mov_b64 s[26:27], -1
	s_and_b64 vcc, exec, s[36:37]
	s_cbranch_vccz .LBB0_1083
	s_lshl_b64 s[26:27], s[34:35], 17
	s_lshl_b32 s0, s2, 9
	v_ashrrev_i32_e32 v173, 31, v172
	s_add_u32 s2, s0, s26
	v_lshlrev_b64 v[8:9], 9, v[172:173]
	s_addc_u32 s3, 0, s27
	v_lshl_add_u64 v[8:9], s[2:3], 0, v[8:9]
	s_lshl_b32 s0, s16, 8
	v_readlane_b32 s2, v254, 33
	s_or_b32 s60, s2, s0
	v_lshlrev_b32_e32 v10, 4, v194
	s_lshl_b64 s[2:3], s[60:61], 2
	v_and_b32_e32 v10, 0xf0, v10
	s_add_u32 s2, s42, s2
	v_or_b32_e32 v8, v8, v10
	s_addc_u32 s3, s43, s3
	v_lshl_add_u64 v[8:9], s[2:3], 0, v[8:9]
	s_mov_b64 s[2:3], 0x27fee00
	v_mul_lo_u32 v11, v172, s77
	v_lshl_add_u64 v[8:9], v[8:9], 0, s[2:3]
	v_add3_u32 v10, v11, v10, s97
	s_mov_b32 s0, 0

.LBB0_1092:
	v_mad_u32_u24 v80, v202, s77, v196
	ds_write_b128 v80, v[8:11]
	ds_write_b128 v80, v[164:167] offset:64
	ds_write_b128 v80, v[12:15] offset:128
	ds_write_b128 v80, v[168:171] offset:192
	v_mov_b64_e32 v[8:9], s[28:29]
	s_movk_i32 s0, 0x300
	v_mad_i64_i32 v[8:9], s[2:3], v86, s0, v[8:9]
	s_lshl_b32 s0, s16, 8
	v_readlane_b32 s2, v254, 33
	s_or_b32 s60, s2, s0
	v_and_b32_e32 v10, 7, v194
	s_lshl_b64 s[2:3], s[60:61], 1
	v_lshlrev_b32_e32 v80, 4, v10
	s_add_u32 s2, s18, s2
	v_lshl_add_u64 v[8:9], v[8:9], 0, v[80:81]
	s_addc_u32 s3, s19, s3
	s_waitcnt lgkmcnt(0)
	v_lshl_add_u64 v[8:9], s[2:3], 0, v[8:9]
	s_mov_b64 s[2:3], 0x4811a00
	v_lshl_add_u64 v[164:165], v[8:9], 0, s[2:3]
	v_mul_lo_u32 v8, v86, s77
	v_lshlrev_b32_e32 v9, 5, v10
	v_add3_u32 v80, v8, v9, s50
	s_mov_b32 s0, 0
	s_mov_b32 s2, 0x3e38aa3b

.LBB0_1095:
	s_andn2_b64 vcc, exec, s[44:45]
	s_cbranch_vccnz .LBB0_1098
	s_lshl_b32 s0, s16, 8
	v_readlane_b32 s2, v254, 33
	v_mad_u32_u24 v8, v202, s77, v196
	v_ashrrev_i32_e32 v87, 31, v86
	s_or_b32 s60, s2, s0
	ds_write_b128 v8, v[82:85]
	ds_write_b128 v8, v[160:163] offset:64
	ds_write_b128 v8, v[152:155] offset:128
	ds_write_b128 v8, v[156:159] offset:192
	v_lshlrev_b64 v[8:9], 9, v[86:87]
	v_and_b32_e32 v10, 7, v194
	s_lshl_b64 s[2:3], s[60:61], 1
	v_lshl_add_u64 v[8:9], v[8:9], 0, s[8:9]
	v_lshlrev_b32_e32 v80, 4, v10
	s_add_u32 s2, s18, s2
	v_lshl_add_u64 v[8:9], v[8:9], 0, v[80:81]
	s_addc_u32 s3, s19, s3
	s_waitcnt lgkmcnt(0)
	v_lshl_add_u64 v[8:9], s[2:3], 0, v[8:9]
	s_mov_b64 s[2:3], 0x440bc00
	v_lshl_add_u64 v[164:165], v[8:9], 0, s[2:3]
	v_mul_lo_u32 v8, v86, s77
	v_lshlrev_b32_e32 v9, 5, v10
	v_add3_u32 v80, v8, v9, s50
	s_mov_b32 s0, 0

.LBB0_1103:
	s_lshl_b32 s0, s16, 8
	v_readlane_b32 s2, v254, 33
	v_mad_u32_u24 v80, v202, s77, v196
	v_ashrrev_i32_e32 v87, 31, v86
	s_or_b32 s60, s2, s0
	ds_write_b128 v80, v[8:11]
	ds_write_b128 v80, v[12:15] offset:64
	ds_write_b128 v80, v[164:167] offset:128
	ds_write_b128 v80, v[168:171] offset:192
	v_lshlrev_b64 v[8:9], 9, v[86:87]
	v_and_b32_e32 v10, 7, v194
	s_lshl_b64 s[2:3], s[60:61], 1
	v_lshl_add_u64 v[8:9], v[8:9], 0, s[8:9]
	v_lshlrev_b32_e32 v80, 4, v10
	s_add_u32 s2, s18, s2
	v_lshl_add_u64 v[8:9], v[8:9], 0, v[80:81]
	s_addc_u32 s3, s19, s3
	s_waitcnt lgkmcnt(0)
	v_lshl_add_u64 v[8:9], s[2:3], 0, v[8:9]
	s_mov_b64 s[2:3], 0x400be00
	v_lshl_add_u64 v[164:165], v[8:9], 0, s[2:3]
	v_mul_lo_u32 v8, v86, s77
	v_lshlrev_b32_e32 v9, 5, v10
	v_add3_u32 v80, v8, v9, s50
	s_mov_b32 s0, 0
	s_mov_b32 s2, 0x3e000000

.LBB0_1109:
	s_lshl_b32 s0, s16, 8
	v_readlane_b32 s2, v254, 33
	s_or_b32 s2, s2, s0
	v_mad_u32_u24 v8, v202, s77, v196
	v_ashrrev_i32_e32 v87, 31, v86
	s_ashr_i32 s3, s2, 31
	ds_write_b128 v8, v[82:85]
	ds_write_b128 v8, v[160:163] offset:64
	ds_write_b128 v8, v[152:155] offset:128
	ds_write_b128 v8, v[156:159] offset:192
	v_lshlrev_b64 v[8:9], 9, v[86:87]
	v_and_b32_e32 v10, 7, v194
	s_lshl_b64 s[2:3], s[2:3], 1
	v_lshl_add_u64 v[8:9], v[8:9], 0, s[8:9]
	v_lshlrev_b32_e32 v80, 4, v10
	s_add_u32 s2, s18, s2
	s_waitcnt lgkmcnt(0)
	v_lshl_add_u64 v[8:9], v[8:9], 0, v[80:81]
	s_addc_u32 s3, s19, s3
	v_lshl_add_u64 v[8:9], s[2:3], 0, v[8:9]
	s_mov_b64 s[2:3], 0x3c0c000
	v_mul_lo_u32 v11, v86, s77
	v_lshlrev_b32_e32 v10, 5, v10
	v_lshl_add_u64 v[8:9], v[8:9], 0, s[2:3]
	v_add3_u32 v10, v11, v10, s50
	s_mov_b32 s0, 0

.LBB0_1112:
	s_cmp_lg_u32 s16, 6
	s_cbranch_scc1 .LBB0_1135
	s_cmp_lg_u32 s58, 13
	s_waitcnt vmcnt(0) lgkmcnt(0)
	s_barrier
	s_cbranch_scc1 .LBB0_1134
	s_lshl_b32 s0, s17, 2
	v_readlane_b32 s2, v254, 10
	s_add_i32 s8, s0, s2
	v_readlane_b32 s0, v255, 10
	s_add_i32 s2, 0, 0x21000
	v_and_b32_e32 v0, -16, v194
	v_mov_b32_e32 v7, s0
	s_movk_i32 s0, 0x80
	v_bitop3_b32 v1, v195, s0, v7 bitop3:0x36
	v_lshl_add_u32 v1, v1, 2, s2
	ds_read_b32 v1, v1
	v_add_u32_e32 v6, s7, v0
	v_add_u32_e32 v84, s97, v0
	v_or_b32_e32 v0, v195, v206
	v_lshlrev_b32_e32 v82, 2, v0
	s_waitcnt lgkmcnt(0)
	v_add_f32_e32 v0, v8, v1
	v_fmamk_f32 v0, v0, 0x3c000000, v180
	v_mul_f32_e32 v1, 0x4b800000, v0
	v_cmp_gt_f32_e32 vcc, s66, v0
	ds_bpermute_b32 v4, v82, v193
	v_mad_u32_u24 v80, v195, s77, v84
	v_cndmask_b32_e32 v0, v0, v1, vcc
	v_rsq_f32_e32 v5, v0
	ds_read_b128 v[0:3], v6
	ds_read_b128 v[152:155], v6 offset:64
	ds_read_b128 v[156:159], v6 offset:128
	ds_read_b128 v[160:163], v6 offset:192
	ds_read_b128 v[164:167], v6 offset:256
	s_movk_i32 s0, 0x90
	v_mul_f32_e32 v8, 0x45800000, v5
	v_cndmask_b32_e32 v8, v5, v8, vcc
	s_waitcnt lgkmcnt(4)
	v_pk_fma_f32 v[2:3], v[150:151], v[4:5], v[2:3] op_sel_hi:[1,0,1]
	v_pk_fma_f32 v[0:1], v[148:149], v[4:5], v[0:1] op_sel_hi:[1,0,1]
	v_pk_mul_f32 v[148:149], v[2:3], v[8:9] op_sel_hi:[1,0]
	v_pk_mul_f32 v[86:87], v[0:1], v[8:9] op_sel_hi:[1,0]
	ds_read_b128 v[0:3], v6 offset:320
	s_waitcnt lgkmcnt(4)
	v_pk_fma_f32 v[144:145], v[144:145], v[4:5], v[152:153] op_sel_hi:[1,0,1]
	s_waitcnt lgkmcnt(1)
	v_pk_mul_f32 v[150:151], v[166:167], v[148:149]
	v_pk_mul_f32 v[144:145], v[144:145], v[8:9] op_sel_hi:[1,0]
	v_pk_mul_f32 v[148:149], v[164:165], v[86:87]
	v_pk_fma_f32 v[86:87], v[146:147], v[4:5], v[154:155] op_sel_hi:[1,0,1]
	s_waitcnt lgkmcnt(0)
	v_pk_mul_f32 v[0:1], v[0:1], v[144:145]
	ds_read_b128 v[144:147], v6 offset:384
	v_pk_mul_f32 v[86:87], v[86:87], v[8:9] op_sel_hi:[1,0]
	v_pk_fma_f32 v[140:141], v[140:141], v[4:5], v[156:157] op_sel_hi:[1,0,1]
	v_pk_mul_f32 v[2:3], v[2:3], v[86:87]
	v_pk_fma_f32 v[86:87], v[142:143], v[4:5], v[158:159] op_sel_hi:[1,0,1]
	v_pk_mul_f32 v[152:153], v[140:141], v[8:9] op_sel_hi:[1,0]
	ds_read_b128 v[140:143], v6 offset:448
	v_pk_mul_f32 v[86:87], v[86:87], v[8:9] op_sel_hi:[1,0]
	s_waitcnt lgkmcnt(1)
	v_pk_mul_f32 v[144:145], v[144:145], v[152:153]
	v_pk_mul_f32 v[146:147], v[146:147], v[86:87]
	v_pk_fma_f32 v[86:87], v[138:139], v[4:5], v[162:163] op_sel_hi:[1,0,1]
	v_pk_fma_f32 v[4:5], v[136:137], v[4:5], v[160:161] op_sel_hi:[1,0,1]
	v_pk_mul_f32 v[86:87], v[86:87], v[8:9] op_sel_hi:[1,0]
	v_pk_mul_f32 v[4:5], v[4:5], v[8:9] op_sel_hi:[1,0]
	s_waitcnt lgkmcnt(0)
	v_pk_mul_f32 v[138:139], v[142:143], v[86:87]
	v_pk_mul_f32 v[136:137], v[140:141], v[4:5]
	ds_write_b128 v80, v[148:151]
	ds_write_b128 v80, v[0:3] offset:64
	ds_write_b128 v80, v[144:147] offset:128
	ds_write_b128 v80, v[136:139] offset:192
	v_bitop3_b32 v0, v195, s0, v7 bitop3:0x36
	v_lshl_add_u32 v0, v0, 2, s2
	s_waitcnt lgkmcnt(0)
	ds_read_b32 v4, v0
	ds_read_b128 v[0:3], v6 offset:64
	ds_read_b128 v[136:139], v6
	ds_read_b128 v[140:143], v6 offset:192
	ds_read_b128 v[144:147], v6 offset:128
	ds_read_b128 v[148:151], v6 offset:256
	v_readlane_b32 s26, v254, 37
	s_waitcnt lgkmcnt(5)
	v_add_f32_e32 v4, v9, v4
	v_fmamk_f32 v4, v4, 0x3c000000, v180
	v_mul_f32_e32 v5, 0x4b800000, v4
	v_cmp_gt_f32_e32 vcc, s66, v4
	v_readlane_b32 s27, v254, 38
	s_ashr_i32 s9, s8, 31
	v_cndmask_b32_e32 v4, v4, v5, vcc
	v_rsq_f32_e32 v5, v4
	ds_bpermute_b32 v4, v82, v193 offset:64
	s_lshl_b64 s[8:9], s[8:9], 17
	v_ashrrev_i32_e32 v173, 31, v172
	v_mul_f32_e32 v7, 0x45800000, v5
	v_cndmask_b32_e32 v8, v5, v7, vcc
	s_waitcnt lgkmcnt(0)
	v_pk_fma_f32 v[132:133], v[132:133], v[4:5], v[136:137] op_sel_hi:[1,0,1]
	v_pk_fma_f32 v[86:87], v[134:135], v[4:5], v[138:139] op_sel_hi:[1,0,1]
	v_pk_mul_f32 v[136:137], v[132:133], v[8:9] op_sel_hi:[1,0]
	ds_read_b128 v[132:135], v6 offset:320
	v_pk_fma_f32 v[2:3], v[130:131], v[4:5], v[2:3] op_sel_hi:[1,0,1]
	v_pk_fma_f32 v[0:1], v[128:129], v[4:5], v[0:1] op_sel_hi:[1,0,1]
	ds_read_b128 v[128:131], v6 offset:384
	v_pk_mul_f32 v[86:87], v[86:87], v[8:9] op_sel_hi:[1,0]
	v_pk_mul_f32 v[0:1], v[0:1], v[8:9] op_sel_hi:[1,0]
	v_pk_fma_f32 v[124:125], v[124:125], v[4:5], v[144:145] op_sel_hi:[1,0,1]
	v_pk_mul_f32 v[138:139], v[150:151], v[86:87]
	s_waitcnt lgkmcnt(1)
	v_pk_mul_f32 v[0:1], v[132:133], v[0:1]
	v_pk_fma_f32 v[86:87], v[126:127], v[4:5], v[146:147] op_sel_hi:[1,0,1]
	v_pk_mul_f32 v[132:133], v[124:125], v[8:9] op_sel_hi:[1,0]
	ds_read_b128 v[124:127], v6 offset:448
	v_pk_mul_f32 v[86:87], v[86:87], v[8:9] op_sel_hi:[1,0]
	v_pk_mul_f32 v[136:137], v[148:149], v[136:137]
	s_waitcnt lgkmcnt(1)
	v_pk_mul_f32 v[130:131], v[130:131], v[86:87]
	v_pk_fma_f32 v[86:87], v[122:123], v[4:5], v[142:143] op_sel_hi:[1,0,1]
	v_pk_fma_f32 v[4:5], v[120:121], v[4:5], v[140:141] op_sel_hi:[1,0,1]
	v_pk_mul_f32 v[2:3], v[2:3], v[8:9] op_sel_hi:[1,0]
	v_pk_mul_f32 v[4:5], v[4:5], v[8:9] op_sel_hi:[1,0]
	v_pk_mul_f32 v[8:9], v[86:87], v[8:9] op_sel_hi:[1,0]
	v_pk_mul_f32 v[2:3], v[134:135], v[2:3]
	v_pk_mul_f32 v[128:129], v[128:129], v[132:133]
	s_waitcnt lgkmcnt(0)
	v_pk_mul_f32 v[122:123], v[126:127], v[8:9]
	v_pk_mul_f32 v[120:121], v[124:125], v[4:5]
	ds_write_b128 v80, v[136:139] offset:4352
	ds_write_b128 v80, v[0:3] offset:4416
	ds_write_b128 v80, v[128:131] offset:4480
	ds_write_b128 v80, v[120:123] offset:4544
	s_nop 1
	v_cndmask_b32_e64 v0, 0, 1, s[26:27]
	v_cmp_ne_u32_e64 s[40:41], 1, v0
	v_lshlrev_b32_e32 v0, 4, v194
	s_andn2_b64 vcc, exec, s[26:27]
	v_mul_lo_u32 v8, v172, s77
	v_and_b32_e32 v0, 0xf0, v0
	v_readlane_b32 s3, v254, 11
	s_cbranch_vccnz .LBB0_1117
	v_readlane_b32 s0, v254, 16
	v_lshlrev_b64 v[2:3], 9, v[172:173]
	s_add_u32 s26, s42, s0
	v_lshl_add_u64 v[2:3], s[8:9], 0, v[2:3]
	v_mov_b32_e32 v1, v81
	s_addc_u32 s27, s43, 0
	v_lshl_add_u64 v[2:3], v[2:3], 0, v[0:1]
	v_lshl_add_u64 v[2:3], s[26:27], 0, v[2:3]
	s_mov_b64 s[26:27], 0x3800000
	v_lshl_add_u64 v[2:3], v[2:3], 0, s[26:27]
	v_add3_u32 v1, v8, v0, s97
	s_mov_b32 s0, 0

.LBB0_1118:
	v_add_u32_e32 v85, -16, v80
	ds_read_b128 v[120:123], v85
	ds_read_b128 v[124:127], v80
	v_lshl_add_u64 v[86:87], v[4:5], 0, s[26:27]
	s_add_u32 s26, s26, 0x800
	s_addc_u32 s27, s27, 0
	s_waitcnt lgkmcnt(1)
	v_cvt_pk_bf16_f32 v120, v120, v121
	v_cvt_pk_bf16_f32 v121, v122, v123
	s_waitcnt lgkmcnt(0)
	v_cvt_pk_bf16_f32 v122, v124, v125
	v_cvt_pk_bf16_f32 v123, v126, v127
	global_store_dwordx4 v[86:87], v[120:123], off sc1
	s_nop 1
	v_add_u32_e32 v80, 0x880, v80
	s_cmpk_lg_i32 s26, 0x2000
	s_cbranch_scc1 .LBB0_1118
	v_xor_b32_e32 v4, 0xa0, v9
	v_lshl_add_u32 v4, v4, 2, s2
	ds_read_b32 v5, v4
	ds_bpermute_b32 v4, v82, v193 offset:128
	ds_read_b128 v[120:123], v6
	ds_read_b128 v[124:127], v6 offset:64
	ds_read_b128 v[128:131], v6 offset:128
	ds_read_b128 v[132:135], v6 offset:192
	ds_read_b128 v[136:139], v6 offset:256
	s_waitcnt lgkmcnt(6)
	v_add_f32_e32 v5, v10, v5
	v_fmamk_f32 v5, v5, 0x3c000000, v180
	v_mul_f32_e32 v10, 0x4b800000, v5
	v_cmp_gt_f32_e32 vcc, s66, v5
	s_nop 1
	v_cndmask_b32_e32 v5, v5, v10, vcc
	v_rsq_f32_e32 v5, v5
	s_nop 0
	v_mul_f32_e32 v10, 0x45800000, v5
	v_cndmask_b32_e32 v10, v5, v10, vcc
	s_waitcnt lgkmcnt(4)
	v_pk_fma_f32 v[116:117], v[116:117], v[4:5], v[120:121] op_sel_hi:[1,0,1]
	v_pk_fma_f32 v[86:87], v[118:119], v[4:5], v[122:123] op_sel_hi:[1,0,1]
	v_pk_mul_f32 v[120:121], v[116:117], v[10:11] op_sel_hi:[1,0]
	ds_read_b128 v[116:119], v6 offset:320
	v_pk_mul_f32 v[86:87], v[86:87], v[10:11] op_sel_hi:[1,0]
	s_waitcnt lgkmcnt(4)
	v_pk_fma_f32 v[112:113], v[112:113], v[4:5], v[124:125] op_sel_hi:[1,0,1]
	s_waitcnt lgkmcnt(1)
	v_pk_mul_f32 v[122:123], v[138:139], v[86:87]
	v_pk_fma_f32 v[86:87], v[114:115], v[4:5], v[126:127] op_sel_hi:[1,0,1]
	v_pk_mul_f32 v[112:113], v[112:113], v[10:11] op_sel_hi:[1,0]
	v_pk_mul_f32 v[86:87], v[86:87], v[10:11] op_sel_hi:[1,0]
	s_waitcnt lgkmcnt(0)
	v_pk_mul_f32 v[112:113], v[116:117], v[112:113]
	v_pk_mul_f32 v[114:115], v[118:119], v[86:87]
	ds_read_b128 v[116:119], v6 offset:384
	v_pk_fma_f32 v[108:109], v[108:109], v[4:5], v[128:129] op_sel_hi:[1,0,1]
	v_pk_fma_f32 v[86:87], v[110:111], v[4:5], v[130:131] op_sel_hi:[1,0,1]
	v_pk_mul_f32 v[124:125], v[108:109], v[10:11] op_sel_hi:[1,0]
	ds_read_b128 v[108:111], v6 offset:448
	v_pk_mul_f32 v[86:87], v[86:87], v[10:11] op_sel_hi:[1,0]
	v_pk_mul_f32 v[120:121], v[136:137], v[120:121]
	s_waitcnt lgkmcnt(1)
	v_pk_mul_f32 v[118:119], v[118:119], v[86:87]
	v_pk_fma_f32 v[86:87], v[106:107], v[4:5], v[134:135] op_sel_hi:[1,0,1]
	v_pk_fma_f32 v[4:5], v[104:105], v[4:5], v[132:133] op_sel_hi:[1,0,1]
	v_pk_mul_f32 v[86:87], v[86:87], v[10:11] op_sel_hi:[1,0]
	v_pk_mul_f32 v[4:5], v[4:5], v[10:11] op_sel_hi:[1,0]
	v_add_u32_e32 v10, v84, v1
	v_xor_b32_e32 v1, 0xb0, v9
	v_pk_mul_f32 v[116:117], v[116:117], v[124:125]
	s_waitcnt lgkmcnt(0)
	v_pk_mul_f32 v[106:107], v[110:111], v[86:87]
	v_pk_mul_f32 v[104:105], v[108:109], v[4:5]
	ds_write_b128 v10, v[120:123]
	ds_write_b128 v10, v[112:115] offset:64
	ds_write_b128 v10, v[116:119] offset:128
	ds_write_b128 v10, v[104:107] offset:192
	v_lshl_add_u32 v1, v1, 2, s2
	s_waitcnt lgkmcnt(0)
	ds_read_b32 v1, v1
	ds_read_b128 v[84:87], v6 offset:64
	ds_read_b128 v[104:107], v6
	ds_read_b128 v[108:111], v6 offset:192
	ds_read_b128 v[112:115], v6 offset:128
	ds_read_b128 v[116:119], v6 offset:256
	s_waitcnt lgkmcnt(5)
	v_add_f32_e32 v1, v11, v1
	v_fmamk_f32 v1, v1, 0x3c000000, v180
	v_mul_f32_e32 v4, 0x4b800000, v1
	v_cmp_gt_f32_e32 vcc, s66, v1
	s_nop 1
	v_cndmask_b32_e32 v1, v1, v4, vcc
	v_rsq_f32_e32 v1, v1
	ds_bpermute_b32 v4, v82, v193 offset:192
	v_mul_f32_e32 v5, 0x45800000, v1
	v_cndmask_b32_e32 v80, v1, v5, vcc
	s_waitcnt lgkmcnt(0)
	v_pk_fma_f32 v[102:103], v[102:103], v[4:5], v[106:107] op_sel_hi:[1,0,1]
	v_pk_fma_f32 v[100:101], v[100:101], v[4:5], v[104:105] op_sel_hi:[1,0,1]
	v_pk_mul_f32 v[106:107], v[102:103], v[80:81] op_sel_hi:[1,0]
	v_pk_mul_f32 v[104:105], v[100:101], v[80:81] op_sel_hi:[1,0]
	ds_read_b128 v[100:103], v6 offset:320
	v_pk_fma_f32 v[86:87], v[98:99], v[4:5], v[86:87] op_sel_hi:[1,0,1]
	v_pk_fma_f32 v[84:85], v[96:97], v[4:5], v[84:85] op_sel_hi:[1,0,1]
	v_pk_mul_f32 v[86:87], v[86:87], v[80:81] op_sel_hi:[1,0]
	v_pk_mul_f32 v[84:85], v[84:85], v[80:81] op_sel_hi:[1,0]
	v_pk_fma_f32 v[94:95], v[94:95], v[4:5], v[114:115] op_sel_hi:[1,0,1]
	v_pk_fma_f32 v[92:93], v[92:93], v[4:5], v[112:113] op_sel_hi:[1,0,1]
	s_waitcnt lgkmcnt(0)
	v_pk_mul_f32 v[86:87], v[102:103], v[86:87]
	v_pk_mul_f32 v[84:85], v[100:101], v[84:85]
	ds_read_b128 v[96:99], v6 offset:384
	v_pk_mul_f32 v[100:101], v[92:93], v[80:81] op_sel_hi:[1,0]
	v_pk_mul_f32 v[102:103], v[94:95], v[80:81] op_sel_hi:[1,0]
	ds_read_b128 v[92:95], v6 offset:448
	v_pk_fma_f32 v[90:91], v[90:91], v[4:5], v[110:111] op_sel_hi:[1,0,1]
	v_pk_fma_f32 v[4:5], v[88:89], v[4:5], v[108:109] op_sel_hi:[1,0,1]
	v_pk_mul_f32 v[106:107], v[118:119], v[106:107]
	v_pk_mul_f32 v[104:105], v[116:117], v[104:105]
	v_pk_mul_f32 v[4:5], v[4:5], v[80:81] op_sel_hi:[1,0]
	v_pk_mul_f32 v[88:89], v[90:91], v[80:81] op_sel_hi:[1,0]
	s_waitcnt lgkmcnt(1)
	v_pk_mul_f32 v[98:99], v[98:99], v[102:103]
	v_pk_mul_f32 v[96:97], v[96:97], v[100:101]
	s_waitcnt lgkmcnt(0)
	v_pk_mul_f32 v[90:91], v[94:95], v[88:89]
	v_pk_mul_f32 v[88:89], v[92:93], v[4:5]
	ds_write_b128 v10, v[104:107] offset:4352
	ds_write_b128 v10, v[84:87] offset:4416
	ds_write_b128 v10, v[96:99] offset:4480
	ds_write_b128 v10, v[88:91] offset:4544
	s_nop 1
	s_and_b64 vcc, exec, s[40:41]
	s_cbranch_vccnz .LBB0_1122
	v_readlane_b32 s0, v254, 52
	s_add_i32 s0, s0, s64
	s_lshl_b32 s0, s0, 9
	s_and_b32 s0, s0, 0x1c000
	v_readlane_b32 s3, v254, 57
	s_add_u32 s26, s42, s3
	s_addc_u32 s27, s43, 0
	s_add_u32 s28, s8, s0
	s_addc_u32 s29, s9, 0
	v_lshlrev_b64 v[4:5], 9, v[172:173]
	v_lshl_add_u64 v[4:5], s[28:29], 0, v[4:5]
	v_mov_b32_e32 v1, v81
	v_lshl_add_u64 v[4:5], v[4:5], 0, v[0:1]
	v_lshl_add_u64 v[4:5], s[26:27], 0, v[4:5]
	s_mov_b64 s[26:27], 0x3800000
	v_lshl_add_u64 v[4:5], v[4:5], 0, s[26:27]
	v_add3_u32 v1, v8, v0, s97
	s_mov_b32 s0, 0

.LBB0_1123:
	v_add_u32_e32 v84, -16, v1
	ds_read_b128 v[84:87], v84
	ds_read_b128 v[88:91], v1
	v_add_u32_e32 v1, 0x880, v1
	s_waitcnt lgkmcnt(1)
	v_cvt_pk_bf16_f32 v84, v84, v85
	v_cvt_pk_bf16_f32 v85, v86, v87
	s_waitcnt lgkmcnt(0)
	v_cvt_pk_bf16_f32 v86, v88, v89
	v_cvt_pk_bf16_f32 v87, v90, v91
	v_lshl_add_u64 v[88:89], v[4:5], 0, s[26:27]
	global_store_dwordx4 v[88:89], v[84:87], off sc1
	s_nop 1
	s_add_u32 s26, s26, 0x800
	s_addc_u32 s27, s27, 0
	s_cmpk_lg_i32 s26, 0x2000
	s_cbranch_scc1 .LBB0_1123
	v_xor_b32_e32 v1, 0xc0, v9
	v_lshl_add_u32 v1, v1, 2, s2
	ds_read_b32 v1, v1
	ds_bpermute_b32 v4, v82, v192
	ds_read_b128 v[84:87], v6
	ds_read_b128 v[88:91], v6 offset:64
	ds_read_b128 v[92:95], v6 offset:128
	ds_read_b128 v[96:99], v6 offset:192
	ds_read_b128 v[100:103], v6 offset:256
	s_waitcnt lgkmcnt(6)
	v_add_f32_e32 v1, v12, v1
	v_fmamk_f32 v1, v1, 0x3c000000, v180
	v_mul_f32_e32 v5, 0x4b800000, v1
	v_cmp_gt_f32_e32 vcc, s66, v1
	s_nop 1
	v_cndmask_b32_e32 v1, v1, v5, vcc
	v_rsq_f32_e32 v1, v1
	s_nop 0
	v_mul_f32_e32 v5, 0x45800000, v1
	v_cndmask_b32_e32 v12, v1, v5, vcc
	s_waitcnt lgkmcnt(4)
	v_pk_fma_f32 v[78:79], v[78:79], v[4:5], v[86:87] op_sel_hi:[1,0,1]
	v_pk_fma_f32 v[76:77], v[76:77], v[4:5], v[84:85] op_sel_hi:[1,0,1]
	v_pk_mul_f32 v[86:87], v[78:79], v[12:13] op_sel_hi:[1,0]
	v_pk_mul_f32 v[84:85], v[76:77], v[12:13] op_sel_hi:[1,0]
	ds_read_b128 v[76:79], v6 offset:320
	s_waitcnt lgkmcnt(4)
	v_pk_fma_f32 v[74:75], v[74:75], v[4:5], v[90:91] op_sel_hi:[1,0,1]
	v_pk_fma_f32 v[72:73], v[72:73], v[4:5], v[88:89] op_sel_hi:[1,0,1]
	v_pk_mul_f32 v[74:75], v[74:75], v[12:13] op_sel_hi:[1,0]
	v_pk_mul_f32 v[72:73], v[72:73], v[12:13] op_sel_hi:[1,0]
	s_waitcnt lgkmcnt(3)
	v_pk_fma_f32 v[70:71], v[70:71], v[4:5], v[94:95] op_sel_hi:[1,0,1]
	v_pk_fma_f32 v[68:69], v[68:69], v[4:5], v[92:93] op_sel_hi:[1,0,1]
	v_pk_mul_f32 v[90:91], v[70:71], v[12:13] op_sel_hi:[1,0]
	v_pk_mul_f32 v[88:89], v[68:69], v[12:13] op_sel_hi:[1,0]
	ds_read_b128 v[68:71], v6 offset:448
	s_waitcnt lgkmcnt(1)
	v_pk_mul_f32 v[74:75], v[78:79], v[74:75]
	v_pk_mul_f32 v[72:73], v[76:77], v[72:73]
	ds_read_b128 v[76:79], v6 offset:384
	v_pk_fma_f32 v[66:67], v[66:67], v[4:5], v[98:99] op_sel_hi:[1,0,1]
	v_pk_fma_f32 v[4:5], v[64:65], v[4:5], v[96:97] op_sel_hi:[1,0,1]
	v_pk_mul_f32 v[86:87], v[102:103], v[86:87]
	v_pk_mul_f32 v[84:85], v[100:101], v[84:85]
	v_pk_mul_f32 v[4:5], v[4:5], v[12:13] op_sel_hi:[1,0]
	v_pk_mul_f32 v[64:65], v[66:67], v[12:13] op_sel_hi:[1,0]
	v_xor_b32_e32 v1, 0xd0, v9
	s_waitcnt lgkmcnt(0)
	v_pk_mul_f32 v[78:79], v[78:79], v[90:91]
	v_pk_mul_f32 v[76:77], v[76:77], v[88:89]
	v_pk_mul_f32 v[66:67], v[70:71], v[64:65]
	v_pk_mul_f32 v[64:65], v[68:69], v[4:5]
	ds_write_b128 v10, v[84:87]
	ds_write_b128 v10, v[72:75] offset:64
	ds_write_b128 v10, v[76:79] offset:128
	ds_write_b128 v10, v[64:67] offset:192
	v_lshl_add_u32 v1, v1, 2, s2
	s_waitcnt lgkmcnt(0)
	ds_read_b32 v1, v1
	ds_read_b128 v[64:67], v6 offset:64
	ds_read_b128 v[68:71], v6
	ds_read_b128 v[72:75], v6 offset:192
	ds_read_b128 v[76:79], v6 offset:128
	s_waitcnt lgkmcnt(4)
	v_add_f32_e32 v1, v13, v1
	v_fmamk_f32 v1, v1, 0x3c000000, v180
	v_mul_f32_e32 v4, 0x4b800000, v1
	v_cmp_gt_f32_e32 vcc, s66, v1
	s_nop 1
	v_cndmask_b32_e32 v1, v1, v4, vcc
	v_rsq_f32_e32 v1, v1
	ds_bpermute_b32 v4, v83, v192
	ds_read_b128 v[82:85], v6 offset:256
	v_mul_f32_e32 v5, 0x45800000, v1
	v_cndmask_b32_e32 v12, v1, v5, vcc
	s_waitcnt lgkmcnt(1)
	v_pk_fma_f32 v[62:63], v[62:63], v[4:5], v[70:71] op_sel_hi:[1,0,1]
	v_pk_fma_f32 v[60:61], v[60:61], v[4:5], v[68:69] op_sel_hi:[1,0,1]
	v_pk_mul_f32 v[70:71], v[62:63], v[12:13] op_sel_hi:[1,0]
	v_pk_mul_f32 v[68:69], v[60:61], v[12:13] op_sel_hi:[1,0]
	ds_read_b128 v[60:63], v6 offset:320
	v_pk_fma_f32 v[58:59], v[58:59], v[4:5], v[66:67] op_sel_hi:[1,0,1]
	v_pk_fma_f32 v[56:57], v[56:57], v[4:5], v[64:65] op_sel_hi:[1,0,1]
	v_pk_mul_f32 v[58:59], v[58:59], v[12:13] op_sel_hi:[1,0]
	v_pk_mul_f32 v[56:57], v[56:57], v[12:13] op_sel_hi:[1,0]
	v_pk_fma_f32 v[54:55], v[54:55], v[4:5], v[78:79] op_sel_hi:[1,0,1]
	v_pk_fma_f32 v[52:53], v[52:53], v[4:5], v[76:77] op_sel_hi:[1,0,1]
	s_waitcnt lgkmcnt(0)
	v_pk_mul_f32 v[58:59], v[62:63], v[58:59]
	v_pk_mul_f32 v[56:57], v[60:61], v[56:57]
	ds_read_b128 v[60:63], v6 offset:384
	v_pk_mul_f32 v[64:65], v[52:53], v[12:13] op_sel_hi:[1,0]
	v_pk_mul_f32 v[66:67], v[54:55], v[12:13] op_sel_hi:[1,0]
	ds_read_b128 v[52:55], v6 offset:448
	v_pk_fma_f32 v[50:51], v[50:51], v[4:5], v[74:75] op_sel_hi:[1,0,1]
	v_pk_fma_f32 v[4:5], v[48:49], v[4:5], v[72:73] op_sel_hi:[1,0,1]
	v_pk_mul_f32 v[70:71], v[84:85], v[70:71]
	v_pk_mul_f32 v[68:69], v[82:83], v[68:69]
	v_pk_mul_f32 v[4:5], v[4:5], v[12:13] op_sel_hi:[1,0]
	v_pk_mul_f32 v[12:13], v[50:51], v[12:13] op_sel_hi:[1,0]
	s_waitcnt lgkmcnt(1)
	v_pk_mul_f32 v[62:63], v[62:63], v[66:67]
	v_pk_mul_f32 v[60:61], v[60:61], v[64:65]
	s_waitcnt lgkmcnt(0)
	v_pk_mul_f32 v[50:51], v[54:55], v[12:13]
	v_pk_mul_f32 v[48:49], v[52:53], v[4:5]
	ds_write_b128 v10, v[68:71] offset:4352
	ds_write_b128 v10, v[56:59] offset:4416
	ds_write_b128 v10, v[60:63] offset:4480
	ds_write_b128 v10, v[48:51] offset:4544
	s_nop 1
	s_and_b64 vcc, exec, s[40:41]
	s_cbranch_vccnz .LBB0_1127
	v_readlane_b32 s0, v254, 53
	s_add_i32 s0, s0, s64
	s_lshl_b32 s0, s0, 9
	s_and_b32 s0, s0, 0x18000
	v_readlane_b32 s3, v254, 57
	s_add_u32 s26, s42, s3
	s_addc_u32 s27, s43, 0
	s_add_u32 s28, s8, s0
	s_addc_u32 s29, s9, 0
	v_lshlrev_b64 v[4:5], 9, v[172:173]
	v_lshl_add_u64 v[4:5], s[28:29], 0, v[4:5]
	v_mov_b32_e32 v1, v81
	v_lshl_add_u64 v[4:5], v[4:5], 0, v[0:1]
	v_lshl_add_u64 v[4:5], s[26:27], 0, v[4:5]
	s_mov_b64 s[26:27], 0x3800000
	v_lshl_add_u64 v[4:5], v[4:5], 0, s[26:27]
	v_add3_u32 v1, v8, v0, s97
	s_mov_b32 s0, 0

.LBB0_1128:
	v_add_u32_e32 v12, -16, v1
	ds_read_b128 v[48:51], v12
	ds_read_b128 v[52:55], v1
	v_lshl_add_u64 v[12:13], v[4:5], 0, s[26:27]
	s_add_u32 s26, s26, 0x800
	s_addc_u32 s27, s27, 0
	s_waitcnt lgkmcnt(1)
	v_cvt_pk_bf16_f32 v48, v48, v49
	v_cvt_pk_bf16_f32 v49, v50, v51
	s_waitcnt lgkmcnt(0)
	v_cvt_pk_bf16_f32 v50, v52, v53
	v_cvt_pk_bf16_f32 v51, v54, v55
	global_store_dwordx4 v[12:13], v[48:51], off sc1
	s_nop 1
	v_add_u32_e32 v1, 0x880, v1
	s_cmpk_lg_i32 s26, 0x2000
	s_cbranch_scc1 .LBB0_1128
	v_xor_b32_e32 v1, 0xe0, v9
	v_lshl_add_u32 v1, v1, 2, s2
	ds_read_b32 v1, v1
	ds_bpermute_b32 v4, v80, v192
	ds_read_b128 v[48:51], v6
	ds_read_b128 v[52:55], v6 offset:64
	ds_read_b128 v[56:59], v6 offset:128
	ds_read_b128 v[60:63], v6 offset:192
	ds_read_b128 v[64:67], v6 offset:256
	s_waitcnt lgkmcnt(6)
	v_add_f32_e32 v1, v14, v1
	v_fmamk_f32 v1, v1, 0x3c000000, v180
	v_mul_f32_e32 v5, 0x4b800000, v1
	v_cmp_gt_f32_e32 vcc, s66, v1
	s_nop 1
	v_cndmask_b32_e32 v1, v1, v5, vcc
	v_rsq_f32_e32 v1, v1
	s_nop 0
	v_mul_f32_e32 v5, 0x45800000, v1
	v_cndmask_b32_e32 v12, v1, v5, vcc
	s_waitcnt lgkmcnt(4)
	v_pk_fma_f32 v[46:47], v[46:47], v[4:5], v[50:51] op_sel_hi:[1,0,1]
	v_pk_fma_f32 v[44:45], v[44:45], v[4:5], v[48:49] op_sel_hi:[1,0,1]
	v_pk_mul_f32 v[50:51], v[46:47], v[12:13] op_sel_hi:[1,0]
	v_pk_mul_f32 v[48:49], v[44:45], v[12:13] op_sel_hi:[1,0]
	ds_read_b128 v[44:47], v6 offset:320
	s_waitcnt lgkmcnt(4)
	v_pk_fma_f32 v[42:43], v[42:43], v[4:5], v[54:55] op_sel_hi:[1,0,1]
	v_pk_fma_f32 v[40:41], v[40:41], v[4:5], v[52:53] op_sel_hi:[1,0,1]
	v_pk_mul_f32 v[42:43], v[42:43], v[12:13] op_sel_hi:[1,0]
	v_pk_mul_f32 v[40:41], v[40:41], v[12:13] op_sel_hi:[1,0]
	s_waitcnt lgkmcnt(3)
	v_pk_fma_f32 v[38:39], v[38:39], v[4:5], v[58:59] op_sel_hi:[1,0,1]
	v_pk_fma_f32 v[36:37], v[36:37], v[4:5], v[56:57] op_sel_hi:[1,0,1]
	v_pk_mul_f32 v[54:55], v[38:39], v[12:13] op_sel_hi:[1,0]
	v_pk_mul_f32 v[52:53], v[36:37], v[12:13] op_sel_hi:[1,0]
	ds_read_b128 v[36:39], v6 offset:448
	s_waitcnt lgkmcnt(1)
	v_pk_mul_f32 v[42:43], v[46:47], v[42:43]
	v_pk_mul_f32 v[40:41], v[44:45], v[40:41]
	ds_read_b128 v[44:47], v6 offset:384
	v_pk_fma_f32 v[34:35], v[34:35], v[4:5], v[62:63] op_sel_hi:[1,0,1]
	v_pk_fma_f32 v[4:5], v[32:33], v[4:5], v[60:61] op_sel_hi:[1,0,1]
	v_pk_mul_f32 v[50:51], v[66:67], v[50:51]
	v_pk_mul_f32 v[48:49], v[64:65], v[48:49]
	v_pk_mul_f32 v[4:5], v[4:5], v[12:13] op_sel_hi:[1,0]
	v_pk_mul_f32 v[12:13], v[34:35], v[12:13] op_sel_hi:[1,0]
	v_xor_b32_e32 v1, 0xf0, v9
	s_waitcnt lgkmcnt(0)
	v_pk_mul_f32 v[46:47], v[46:47], v[54:55]
	v_pk_mul_f32 v[44:45], v[44:45], v[52:53]
	v_pk_mul_f32 v[34:35], v[38:39], v[12:13]
	v_pk_mul_f32 v[32:33], v[36:37], v[4:5]
	ds_write_b128 v10, v[48:51]
	ds_write_b128 v10, v[40:43] offset:64
	ds_write_b128 v10, v[44:47] offset:128
	ds_write_b128 v10, v[32:35] offset:192
	v_lshl_add_u32 v1, v1, 2, s2
	s_waitcnt lgkmcnt(0)
	ds_read_b32 v1, v1
	ds_read_b128 v[32:35], v6 offset:64
	ds_read_b128 v[36:39], v6
	s_waitcnt lgkmcnt(2)
	v_add_f32_e32 v1, v15, v1
	v_fmamk_f32 v1, v1, 0x3c000000, v180
	v_mul_f32_e32 v4, 0x4b800000, v1
	v_cmp_gt_f32_e32 vcc, s66, v1
	ds_read_b128 v[12:15], v6 offset:192
	ds_read_b128 v[40:43], v6 offset:128
	v_cndmask_b32_e32 v1, v1, v4, vcc
	v_rsq_f32_e32 v1, v1
	ds_bpermute_b32 v4, v11, v192
	ds_read_b128 v[44:47], v6 offset:256
	v_mul_f32_e32 v5, 0x45800000, v1
	v_cndmask_b32_e32 v48, v1, v5, vcc
	s_waitcnt lgkmcnt(1)
	v_pk_fma_f32 v[30:31], v[30:31], v[4:5], v[38:39] op_sel_hi:[1,0,1]
	v_pk_fma_f32 v[28:29], v[28:29], v[4:5], v[36:37] op_sel_hi:[1,0,1]
	v_pk_mul_f32 v[38:39], v[30:31], v[48:49] op_sel_hi:[1,0]
	v_pk_mul_f32 v[36:37], v[28:29], v[48:49] op_sel_hi:[1,0]
	ds_read_b128 v[28:31], v6 offset:320
	v_pk_fma_f32 v[26:27], v[26:27], v[4:5], v[34:35] op_sel_hi:[1,0,1]
	v_pk_fma_f32 v[24:25], v[24:25], v[4:5], v[32:33] op_sel_hi:[1,0,1]
	v_pk_mul_f32 v[26:27], v[26:27], v[48:49] op_sel_hi:[1,0]
	v_pk_mul_f32 v[24:25], v[24:25], v[48:49] op_sel_hi:[1,0]
	v_pk_fma_f32 v[18:19], v[18:19], v[4:5], v[42:43] op_sel_hi:[1,0,1]
	v_pk_fma_f32 v[16:17], v[16:17], v[4:5], v[40:41] op_sel_hi:[1,0,1]
	s_waitcnt lgkmcnt(0)
	v_pk_mul_f32 v[26:27], v[30:31], v[26:27]
	v_pk_mul_f32 v[24:25], v[28:29], v[24:25]
	ds_read_b128 v[28:31], v6 offset:384
	v_pk_mul_f32 v[32:33], v[16:17], v[48:49] op_sel_hi:[1,0]
	v_pk_mul_f32 v[34:35], v[18:19], v[48:49] op_sel_hi:[1,0]
	ds_read_b128 v[16:19], v6 offset:448
	v_pk_fma_f32 v[14:15], v[22:23], v[4:5], v[14:15] op_sel_hi:[1,0,1]
	v_pk_fma_f32 v[4:5], v[20:21], v[4:5], v[12:13] op_sel_hi:[1,0,1]
	v_pk_mul_f32 v[38:39], v[46:47], v[38:39]
	v_pk_mul_f32 v[36:37], v[44:45], v[36:37]
	v_pk_mul_f32 v[4:5], v[4:5], v[48:49] op_sel_hi:[1,0]
	v_pk_mul_f32 v[12:13], v[14:15], v[48:49] op_sel_hi:[1,0]
	s_waitcnt lgkmcnt(1)
	v_pk_mul_f32 v[30:31], v[30:31], v[34:35]
	v_pk_mul_f32 v[28:29], v[28:29], v[32:33]
	s_waitcnt lgkmcnt(0)
	v_pk_mul_f32 v[14:15], v[18:19], v[12:13]
	v_pk_mul_f32 v[12:13], v[16:17], v[4:5]
	ds_write_b128 v10, v[36:39] offset:4352
	ds_write_b128 v10, v[24:27] offset:4416
	ds_write_b128 v10, v[28:31] offset:4480
	ds_write_b128 v10, v[12:15] offset:4544
	s_nop 1
	s_and_b64 vcc, exec, s[40:41]
	s_cbranch_vccnz .LBB0_1132
	v_readlane_b32 s0, v255, 12
	s_add_i32 s0, s0, s64
	s_lshl_b32 s0, s0, 9
	s_and_b32 s0, s0, 0x1c000
	v_readlane_b32 s2, v254, 57
	s_add_u32 s2, s42, s2
	s_addc_u32 s3, s43, 0
	s_add_u32 s8, s8, s0
	s_addc_u32 s9, s9, 0
	v_lshlrev_b64 v[4:5], 9, v[172:173]
	v_lshl_add_u64 v[4:5], s[8:9], 0, v[4:5]
	v_mov_b32_e32 v1, v81
	v_lshl_add_u64 v[4:5], v[4:5], 0, v[0:1]
	v_lshl_add_u64 v[4:5], s[2:3], 0, v[4:5]
	s_mov_b64 s[2:3], 0x3800000
	v_lshl_add_u64 v[4:5], v[4:5], 0, s[2:3]
	v_add3_u32 v0, v8, v0, s97
	s_mov_b32 s0, 0

.LBB0_1169:
	v_add_u32_e32 v79, s97, v71
	v_mad_u32_u24 v71, v78, s77, v79
	s_mov_b32 s60, s61
	ds_write_b128 v71, v[60:63]
	ds_write_b128 v71, v[56:59] offset:64
	s_mov_b32 s62, s61
	s_mov_b32 s63, s61
	v_mov_b64_e32 v[56:57], s[60:61]
	v_mov_b64_e32 v[58:59], s[62:63]
	ds_write_b128 v71, v[56:59] offset:128
	ds_write_b128 v71, v[56:59] offset:192
	v_or_b32_e32 v71, 16, v78
	v_or_b32_e32 v56, v71, v206
	v_lshlrev_b32_e32 v74, 2, v56
	ds_bpermute_b32 v80, v74, v85
	s_waitcnt lgkmcnt(0)
	ds_read_b128 v[56:59], v66
	ds_read_b128 v[60:63], v66 offset:64
	s_andn2_b64 vcc, exec, s[18:19]
	s_waitcnt lgkmcnt(1)
	v_pk_fma_f32 v[48:49], v[48:49], v[80:81], v[56:57] op_sel_hi:[1,0,1]
	v_cndmask_b32_e64 v56, 0, 1, s[18:19]
	v_cmp_ne_u32_e64 s[44:45], 1, v56
	v_cvt_f32_ubyte0_e32 v56, v71
	v_pk_fma_f32 v[50:51], v[50:51], v[80:81], v[58:59] op_sel_hi:[1,0,1]
	s_waitcnt lgkmcnt(0)
	v_pk_fma_f32 v[52:53], v[52:53], v[80:81], v[60:61] op_sel_hi:[1,0,1]
	v_pk_fma_f32 v[54:55], v[54:55], v[80:81], v[62:63] op_sel_hi:[1,0,1]
	v_mul_f32_e32 v73, v68, v56
	v_mul_f32_e32 v71, v67, v56
	v_mul_f32_e32 v62, v65, v56
	v_mul_f32_e32 v60, v64, v56
	s_cbranch_vccnz .LBB0_1171
	s_lshr_b32 s0, s26, 6
	s_and_b32 s0, s0, 14
	v_cvt_f32_ubyte0_e32 v61, s0
	v_mul_f32_e32 v56, v68, v61
	v_sin_f32_e32 v63, v56
	v_mul_f32_e32 v57, v67, v61
	ds_bpermute_b32 v58, v219, v48
	v_sin_f32_e32 v83, v57
	ds_bpermute_b32 v59, v219, v49
	v_cndmask_b32_e64 v88, -v63, v63, s[40:41]
	v_sin_f32_e32 v63, v71
	v_sin_f32_e32 v80, v73
	ds_bpermute_b32 v86, v219, v52
	v_cndmask_b32_e64 v89, -v83, v83, s[40:41]
	ds_bpermute_b32 v87, v219, v53
	s_waitcnt lgkmcnt(2)
	v_pk_mul_f32 v[58:59], v[88:89], v[58:59]
	v_cndmask_b32_e64 v89, -v63, v63, s[40:41]
	v_mul_f32_e32 v63, v65, v61
	v_cndmask_b32_e64 v88, -v80, v80, s[40:41]
	v_cos_f32_e32 v80, v63
	v_sin_f32_e32 v63, v63
	s_waitcnt lgkmcnt(0)
	v_pk_mul_f32 v[86:87], v[88:89], v[86:87]
	ds_bpermute_b32 v88, v219, v50
	v_cos_f32_e32 v56, v56
	v_cos_f32_e32 v57, v57
	v_mul_f32_e32 v50, v80, v50
	v_cos_f32_e32 v80, v62
	v_sin_f32_e32 v89, v62
	v_cndmask_b32_e64 v63, -v63, v63, s[40:41]
	v_mul_f32_e32 v61, v64, v61
	s_waitcnt lgkmcnt(0)
	v_mul_f32_e32 v88, v63, v88
	ds_bpermute_b32 v63, v219, v54
	v_mul_f32_e32 v54, v80, v54
	v_cndmask_b32_e64 v80, -v89, v89, s[40:41]
	v_sin_f32_e32 v89, v61
	ds_bpermute_b32 v91, v219, v51
	v_pk_fma_f32 v[48:49], v[56:57], v[48:49], v[58:59]
	v_sin_f32_e32 v56, v60
	ds_bpermute_b32 v57, v219, v55
	v_cos_f32_e32 v92, v61
	v_cos_f32_e32 v58, v60
	v_cos_f32_e32 v82, v73
	v_cos_f32_e32 v83, v71
	v_cndmask_b32_e64 v93, -v89, v89, s[40:41]
	v_mov_b32_e32 v90, v51
	v_cndmask_b32_e64 v59, -v56, v56, s[40:41]
	v_mov_b32_e32 v56, v55
	s_waitcnt lgkmcnt(1)
	v_pk_mul_f32 v[90:91], v[92:93], v[90:91]
	s_waitcnt lgkmcnt(0)
	v_pk_mul_f32 v[56:57], v[58:59], v[56:57]
	v_mul_f32_e32 v94, v80, v63
	v_mov_b32_e32 v51, v90
	v_mov_b32_e32 v89, v91
	v_mov_b32_e32 v55, v56
	v_mov_b32_e32 v95, v57
	v_pk_add_f32 v[50:51], v[50:51], v[88:89]
	v_pk_fma_f32 v[52:53], v[82:83], v[52:53], v[86:87]
	v_pk_add_f32 v[54:55], v[54:55], v[94:95]
.LBB0_1171:
	v_mul_u32_u24_e32 v57, 0x110, v78
	s_add_i32 s0, s51, -16
	s_lshr_b32 s0, s0, 2
	v_add_u32_e32 v59, v57, v79
	s_and_b64 s[2:3], s[18:19], exec
	ds_write_b128 v59, v[48:51] offset:4352
	ds_write_b128 v59, v[52:55] offset:4416
	v_mov_b64_e32 v[48:49], s[60:61]
	s_cselect_b32 s0, s0, s51
	v_mov_b64_e32 v[50:51], s[62:63]
	s_lshl_b32 s0, s0, 2
	v_readlane_b32 s2, v254, 10
	ds_write_b128 v59, v[48:51] offset:4480
	ds_write_b128 v59, v[48:51] offset:4544
	v_readlane_b32 s3, v254, 11
	s_add_i32 s2, s0, s2
	s_waitcnt lgkmcnt(0)
	v_cndmask_b32_e64 v48, 0, 1, s[34:35]
	s_ashr_i32 s3, s2, 31
	v_ashrrev_i32_e32 v56, 3, v70
	v_cmp_ne_u32_e64 s[42:43], 1, v48
	v_lshlrev_b32_e32 v48, 4, v70
	s_lshl_b64 s[18:19], s[2:3], 15
	s_andn2_b64 vcc, exec, s[34:35]
	v_ashrrev_i32_e32 v57, 31, v56
	v_mul_lo_u32 v58, v56, s77
	v_and_b32_e32 v50, 0x70, v48
	s_cbranch_vccnz .LBB0_1174
	v_readlane_b32 s0, v255, 23
	v_lshlrev_b64 v[48:49], 7, v[56:57]
	s_add_u32 s2, s8, s0
	v_lshl_add_u64 v[48:49], s[18:19], 0, v[48:49]
	v_mov_b32_e32 v51, v81
	s_addc_u32 s3, s9, 0
	v_lshl_add_u64 v[48:49], v[48:49], 0, v[50:51]
	v_lshl_add_u64 v[48:49], s[2:3], 0, v[48:49]
	s_mov_b64 s[2:3], 0x4000000
	v_lshl_add_u64 v[48:49], v[48:49], 0, s[2:3]
	v_add3_u32 v51, v58, v50, s97
	s_mov_b32 s0, 0

.LBB0_1178:
	s_mov_b32 s60, s61
	ds_write_b128 v59, v[44:47]
	ds_write_b128 v59, v[40:43] offset:64
	s_mov_b32 s62, s61
	s_mov_b32 s63, s61
	v_mov_b64_e32 v[40:41], s[60:61]
	v_mov_b64_e32 v[42:43], s[62:63]
	v_or_b32_e32 v45, 48, v78
	ds_write_b128 v59, v[40:43] offset:128
	ds_write_b128 v59, v[40:43] offset:192
	v_or_b32_e32 v40, v45, v206
	v_lshlrev_b32_e32 v44, 2, v40
	ds_bpermute_b32 v46, v44, v85
	s_waitcnt lgkmcnt(0)
	ds_read_b128 v[40:43], v66
	ds_read_b128 v[86:89], v66 offset:64
	s_and_b64 vcc, exec, s[44:45]
	s_waitcnt lgkmcnt(1)
	v_pk_fma_f32 v[32:33], v[32:33], v[46:47], v[40:41] op_sel_hi:[1,0,1]
	v_cvt_f32_ubyte0_e32 v40, v45
	v_pk_fma_f32 v[34:35], v[34:35], v[46:47], v[42:43] op_sel_hi:[1,0,1]
	s_waitcnt lgkmcnt(0)
	v_pk_fma_f32 v[36:37], v[36:37], v[46:47], v[86:87] op_sel_hi:[1,0,1]
	v_pk_fma_f32 v[38:39], v[38:39], v[46:47], v[88:89] op_sel_hi:[1,0,1]
	v_mul_f32_e32 v43, v68, v40
	v_mul_f32_e32 v42, v67, v40
	v_mul_f32_e32 v41, v65, v40
	v_mul_f32_e32 v40, v64, v40
	s_cbranch_vccnz .LBB0_1180
	s_lshr_b32 s0, s26, 6
	s_and_b32 s0, s0, 14
	v_cvt_f32_ubyte0_e32 v45, s0
	v_mul_f32_e32 v46, v68, v45
	v_sin_f32_e32 v51, v46
	v_mul_f32_e32 v47, v67, v45
	ds_bpermute_b32 v78, v219, v32
	v_sin_f32_e32 v83, v47
	ds_bpermute_b32 v79, v219, v33
	v_cndmask_b32_e64 v88, -v51, v51, s[40:41]
	v_sin_f32_e32 v51, v42
	v_sin_f32_e32 v80, v43
	v_cndmask_b32_e64 v89, -v83, v83, s[40:41]
	s_waitcnt lgkmcnt(0)
	v_pk_mul_f32 v[78:79], v[88:89], v[78:79]
	v_cndmask_b32_e64 v89, -v51, v51, s[40:41]
	v_mul_f32_e32 v51, v65, v45
	ds_bpermute_b32 v86, v219, v36
	ds_bpermute_b32 v87, v219, v37
	v_cndmask_b32_e64 v88, -v80, v80, s[40:41]
	v_cos_f32_e32 v80, v51
	v_sin_f32_e32 v51, v51
	ds_bpermute_b32 v85, v219, v34
	v_cos_f32_e32 v46, v46
	v_cos_f32_e32 v47, v47
	v_cndmask_b32_e64 v51, -v51, v51, s[40:41]
	v_mul_f32_e32 v45, v64, v45
	s_waitcnt lgkmcnt(1)
	v_pk_mul_f32 v[86:87], v[88:89], v[86:87]
	s_waitcnt lgkmcnt(0)
	v_mul_f32_e32 v88, v51, v85
	v_sin_f32_e32 v85, v45
	ds_bpermute_b32 v91, v219, v35
	v_cos_f32_e32 v92, v45
	v_pk_fma_f32 v[32:33], v[46:47], v[32:33], v[78:79]
	v_sin_f32_e32 v45, v40
	ds_bpermute_b32 v47, v219, v39
	v_mul_f32_e32 v34, v80, v34
	v_cos_f32_e32 v80, v41
	v_sin_f32_e32 v89, v41
	ds_bpermute_b32 v51, v219, v38
	v_cos_f32_e32 v78, v40
	v_cos_f32_e32 v82, v43
	v_cos_f32_e32 v83, v42
	v_cndmask_b32_e64 v93, -v85, v85, s[40:41]
	v_mov_b32_e32 v90, v35
	v_cndmask_b32_e64 v79, -v45, v45, s[40:41]
	v_mov_b32_e32 v46, v39
	v_mul_f32_e32 v38, v80, v38
	v_cndmask_b32_e64 v80, -v89, v89, s[40:41]
	s_waitcnt lgkmcnt(2)
	v_pk_mul_f32 v[90:91], v[92:93], v[90:91]
	s_waitcnt lgkmcnt(1)
	v_pk_mul_f32 v[46:47], v[78:79], v[46:47]
	s_waitcnt lgkmcnt(0)
	v_mul_f32_e32 v94, v80, v51
	v_mov_b32_e32 v35, v90
	v_mov_b32_e32 v89, v91
	v_mov_b32_e32 v39, v46
	v_mov_b32_e32 v95, v47
	v_pk_add_f32 v[34:35], v[34:35], v[88:89]
	v_pk_fma_f32 v[36:37], v[82:83], v[36:37], v[86:87]
	v_pk_add_f32 v[38:39], v[38:39], v[94:95]
.LBB0_1180:
	ds_write_b128 v59, v[32:35] offset:4352
	ds_write_b128 v59, v[36:39] offset:4416
	v_mov_b64_e32 v[32:33], s[60:61]
	v_mov_b64_e32 v[34:35], s[62:63]
	ds_write_b128 v59, v[32:35] offset:4480
	ds_write_b128 v59, v[32:35] offset:4544
	s_nop 1
	s_and_b64 vcc, exec, s[42:43]
	s_cbranch_vccnz .LBB0_1183
	v_readlane_b32 s0, v255, 24
	s_add_i32 s0, s0, s64
	s_lshl_b32 s0, s0, 7
	s_and_b32 s0, s0, 0x7000
	s_add_u32 s2, s18, s0
	s_addc_u32 s3, s19, 0
	v_lshlrev_b64 v[32:33], 7, v[56:57]
	v_lshl_add_u64 v[32:33], s[2:3], 0, v[32:33]
	v_mov_b32_e32 v51, v81
	v_lshl_add_u64 v[32:33], v[32:33], 0, v[50:51]
	v_lshl_add_u64 v[32:33], s[8:9], 0, v[32:33]
	s_mov_b64 s[2:3], 0x4000000
	v_lshl_add_u64 v[32:33], v[32:33], 0, s[2:3]
	v_add3_u32 v34, v58, v50, s97
	s_mov_b32 s0, 0

.LBB0_1187:
	s_mov_b32 s60, s61
	ds_write_b128 v59, v[28:31]
	ds_write_b128 v59, v[24:27] offset:64
	s_mov_b32 s62, s61
	s_mov_b32 s63, s61
	v_mov_b64_e32 v[24:25], s[60:61]
	v_mov_b64_e32 v[26:27], s[62:63]
	ds_write_b128 v59, v[24:27] offset:128
	ds_write_b128 v59, v[24:27] offset:192
	s_nop 1
	ds_bpermute_b32 v32, v74, v84
	ds_read_b128 v[24:27], v66
	ds_read_b128 v[28:31], v66 offset:64
	s_and_b64 vcc, exec, s[44:45]
	s_waitcnt lgkmcnt(1)
	v_pk_fma_f32 v[16:17], v[16:17], v[32:33], v[24:25] op_sel_hi:[1,0,1]
	v_pk_fma_f32 v[18:19], v[18:19], v[32:33], v[26:27] op_sel_hi:[1,0,1]
	s_waitcnt lgkmcnt(0)
	v_pk_fma_f32 v[20:21], v[20:21], v[32:33], v[28:29] op_sel_hi:[1,0,1]
	v_pk_fma_f32 v[22:23], v[22:23], v[32:33], v[30:31] op_sel_hi:[1,0,1]
	s_cbranch_vccnz .LBB0_1189
	s_bfe_u32 s0, s28, 0x40006
	v_cvt_f32_ubyte0_e32 v35, s0
	v_mul_f32_e32 v24, v68, v35
	v_mul_f32_e32 v25, v67, v35
	v_sin_f32_e32 v29, v24
	ds_bpermute_b32 v26, v219, v16
	v_sin_f32_e32 v31, v25
	ds_bpermute_b32 v27, v219, v17
	v_cndmask_b32_e64 v32, -v29, v29, s[40:41]
	v_sin_f32_e32 v34, v73
	v_cndmask_b32_e64 v33, -v31, v31, s[40:41]
	ds_bpermute_b32 v30, v219, v20
	s_waitcnt lgkmcnt(1)
	v_pk_mul_f32 v[26:27], v[32:33], v[26:27]
	v_sin_f32_e32 v32, v71
	ds_bpermute_b32 v31, v219, v21
	ds_bpermute_b32 v36, v219, v22
	v_cos_f32_e32 v24, v24
	v_cndmask_b32_e64 v33, -v32, v32, s[40:41]
	v_cndmask_b32_e64 v32, -v34, v34, s[40:41]
	s_waitcnt lgkmcnt(1)
	v_pk_mul_f32 v[30:31], v[32:33], v[30:31]
	v_mul_f32_e32 v32, v65, v35
	v_sin_f32_e32 v33, v32
	v_cos_f32_e32 v32, v32
	ds_bpermute_b32 v34, v219, v18
	v_cos_f32_e32 v25, v25
	ds_bpermute_b32 v39, v219, v19
	v_mul_f32_e32 v18, v32, v18
	v_cndmask_b32_e64 v32, -v33, v33, s[40:41]
	v_sin_f32_e32 v33, v62
	s_waitcnt lgkmcnt(1)
	v_mul_f32_e32 v32, v32, v34
	v_cos_f32_e32 v34, v62
	v_pk_fma_f32 v[16:17], v[24:25], v[16:17], v[26:27]
	v_cndmask_b32_e64 v33, -v33, v33, s[40:41]
	v_sin_f32_e32 v25, v60
	v_mul_f32_e32 v22, v34, v22
	v_mul_f32_e32 v34, v33, v36
	v_mul_f32_e32 v33, v64, v35
	v_sin_f32_e32 v35, v33
	ds_bpermute_b32 v27, v219, v23
	v_cos_f32_e32 v36, v33
	v_cos_f32_e32 v24, v60
	v_cos_f32_e32 v28, v73
	v_cos_f32_e32 v29, v71
	v_cndmask_b32_e64 v37, -v35, v35, s[40:41]
	v_mov_b32_e32 v38, v19
	v_cndmask_b32_e64 v25, -v25, v25, s[40:41]
	v_mov_b32_e32 v26, v23
	s_waitcnt lgkmcnt(1)
	v_pk_mul_f32 v[36:37], v[36:37], v[38:39]
	s_waitcnt lgkmcnt(0)
	v_pk_mul_f32 v[24:25], v[24:25], v[26:27]
	v_mov_b32_e32 v19, v36
	v_mov_b32_e32 v33, v37
	v_mov_b32_e32 v23, v24
	v_mov_b32_e32 v35, v25
	v_pk_add_f32 v[18:19], v[18:19], v[32:33]
	v_pk_fma_f32 v[20:21], v[28:29], v[20:21], v[30:31]
	v_pk_add_f32 v[22:23], v[22:23], v[34:35]
.LBB0_1189:
	ds_write_b128 v59, v[16:19] offset:4352
	ds_write_b128 v59, v[20:23] offset:4416
	v_mov_b64_e32 v[16:17], s[60:61]
	v_mov_b64_e32 v[18:19], s[62:63]
	ds_write_b128 v59, v[16:19] offset:4480
	ds_write_b128 v59, v[16:19] offset:4544
	s_nop 1
	s_and_b64 vcc, exec, s[42:43]
	s_cbranch_vccnz .LBB0_1192
	v_readlane_b32 s0, v255, 25
	s_add_i32 s0, s0, s64
	s_lshl_b32 s0, s0, 7
	s_and_b32 s0, s0, 0x6000
	s_add_u32 s2, s18, s0
	s_addc_u32 s3, s19, 0
	v_lshlrev_b64 v[16:17], 7, v[56:57]
	v_lshl_add_u64 v[16:17], s[2:3], 0, v[16:17]
	v_mov_b32_e32 v51, v81
	v_lshl_add_u64 v[16:17], v[16:17], 0, v[50:51]
	v_lshl_add_u64 v[16:17], s[8:9], 0, v[16:17]
	s_mov_b64 s[2:3], 0x4000000
	v_lshl_add_u64 v[16:17], v[16:17], 0, s[2:3]
	v_add3_u32 v18, v58, v50, s97
	s_mov_b32 s0, 0

.LBB0_1196:
	s_mov_b32 s60, s61
	ds_write_b128 v59, v[12:15]
	ds_write_b128 v59, v[8:11] offset:64
	s_mov_b32 s62, s61
	s_mov_b32 s63, s61
	v_mov_b64_e32 v[8:9], s[60:61]
	v_mov_b64_e32 v[10:11], s[62:63]
	ds_write_b128 v59, v[8:11] offset:128
	ds_write_b128 v59, v[8:11] offset:192
	s_nop 1
	ds_bpermute_b32 v16, v44, v84
	ds_read_b128 v[8:11], v66
	ds_read_b128 v[12:15], v66 offset:64
	s_and_b64 vcc, exec, s[44:45]
	s_waitcnt lgkmcnt(1)
	v_pk_fma_f32 v[4:5], v[4:5], v[16:17], v[8:9] op_sel_hi:[1,0,1]
	v_pk_fma_f32 v[6:7], v[6:7], v[16:17], v[10:11] op_sel_hi:[1,0,1]
	s_waitcnt lgkmcnt(0)
	v_pk_fma_f32 v[0:1], v[0:1], v[16:17], v[12:13] op_sel_hi:[1,0,1]
	v_pk_fma_f32 v[2:3], v[2:3], v[16:17], v[14:15] op_sel_hi:[1,0,1]
	s_cbranch_vccnz .LBB0_1198
	s_bfe_u32 s0, s26, 0x40006
	v_cvt_f32_ubyte0_e32 v19, s0
	v_mul_f32_e32 v8, v68, v19
	v_mul_f32_e32 v9, v67, v19
	v_sin_f32_e32 v13, v8
	ds_bpermute_b32 v10, v219, v4
	v_sin_f32_e32 v15, v9
	ds_bpermute_b32 v11, v219, v5
	v_cndmask_b32_e64 v16, -v13, v13, s[40:41]
	v_sin_f32_e32 v18, v43
	v_cndmask_b32_e64 v17, -v15, v15, s[40:41]
	ds_bpermute_b32 v14, v219, v0
	s_waitcnt lgkmcnt(1)
	v_pk_mul_f32 v[10:11], v[16:17], v[10:11]
	v_sin_f32_e32 v16, v42
	ds_bpermute_b32 v15, v219, v1
	ds_bpermute_b32 v20, v219, v2
	v_cos_f32_e32 v8, v8
	v_cndmask_b32_e64 v17, -v16, v16, s[40:41]
	v_cndmask_b32_e64 v16, -v18, v18, s[40:41]
	s_waitcnt lgkmcnt(1)
	v_pk_mul_f32 v[14:15], v[16:17], v[14:15]
	v_mul_f32_e32 v16, v65, v19
	v_sin_f32_e32 v17, v16
	v_cos_f32_e32 v16, v16
	ds_bpermute_b32 v18, v219, v6
	v_cos_f32_e32 v9, v9
	ds_bpermute_b32 v23, v219, v7
	v_mul_f32_e32 v6, v16, v6
	v_cndmask_b32_e64 v16, -v17, v17, s[40:41]
	v_sin_f32_e32 v17, v41
	s_waitcnt lgkmcnt(1)
	v_mul_f32_e32 v16, v16, v18
	v_cos_f32_e32 v18, v41
	v_pk_fma_f32 v[4:5], v[8:9], v[4:5], v[10:11]
	v_cndmask_b32_e64 v17, -v17, v17, s[40:41]
	v_sin_f32_e32 v9, v40
	v_mul_f32_e32 v2, v18, v2
	v_mul_f32_e32 v18, v17, v20
	v_mul_f32_e32 v17, v64, v19
	v_sin_f32_e32 v19, v17
	ds_bpermute_b32 v11, v219, v3
	v_cos_f32_e32 v20, v17
	v_cos_f32_e32 v8, v40
	v_cos_f32_e32 v12, v43
	v_cos_f32_e32 v13, v42
	v_cndmask_b32_e64 v21, -v19, v19, s[40:41]
	v_mov_b32_e32 v22, v7
	v_cndmask_b32_e64 v9, -v9, v9, s[40:41]
	v_mov_b32_e32 v10, v3
	s_waitcnt lgkmcnt(1)
	v_pk_mul_f32 v[20:21], v[20:21], v[22:23]
	s_waitcnt lgkmcnt(0)
	v_pk_mul_f32 v[8:9], v[8:9], v[10:11]
	v_mov_b32_e32 v7, v20
	v_mov_b32_e32 v17, v21
	v_mov_b32_e32 v3, v8
	v_mov_b32_e32 v19, v9
	v_pk_add_f32 v[6:7], v[6:7], v[16:17]
	v_pk_fma_f32 v[0:1], v[12:13], v[0:1], v[14:15]
	v_pk_add_f32 v[2:3], v[2:3], v[18:19]
.LBB0_1198:
	ds_write_b128 v59, v[4:7] offset:4352
	ds_write_b128 v59, v[0:3] offset:4416
	v_mov_b64_e32 v[0:1], s[60:61]
	v_mov_b64_e32 v[2:3], s[62:63]
	ds_write_b128 v59, v[0:3] offset:4480
	ds_write_b128 v59, v[0:3] offset:4544
	s_nop 1
	v_readlane_b32 s44, v254, 36
	s_and_b64 vcc, exec, s[42:43]
	s_cbranch_vccnz .LBB0_1201
	v_readlane_b32 s0, v255, 26
	s_add_i32 s0, s0, s64
	s_lshl_b32 s0, s0, 7
	s_and_b32 s0, s0, 0x7000
	s_add_u32 s2, s18, s0
	s_addc_u32 s3, s19, 0
	v_lshlrev_b64 v[0:1], 7, v[56:57]
	v_lshl_add_u64 v[0:1], s[2:3], 0, v[0:1]
	v_mov_b32_e32 v51, v81
	v_lshl_add_u64 v[0:1], v[0:1], 0, v[50:51]
	v_lshl_add_u64 v[0:1], s[8:9], 0, v[0:1]
	s_mov_b64 s[2:3], 0x4000000
	v_lshl_add_u64 v[0:1], v[0:1], 0, s[2:3]
	v_add3_u32 v2, v58, v50, s97
	s_mov_b32 s0, 0

.LBB0_1393:
	s_lshl_b32 s0, s0, 8
	v_mov_b32_e32 v66, v188
	s_and_b32 s0, s0, 0x600
	s_lshl_b32 s40, s79, 8
	s_and_b32 s40, s40, 0x100
	v_and_b32_e32 v65, -16, v66
	v_and_b32_e32 v64, 15, v66
	v_add_u32_e32 v73, s78, v65
	s_add_i32 s0, s66, s0
	v_mul_u32_u24_e32 v75, 0x110, v64
	v_mad_u32_u24 v64, v64, s77, v73
	s_add_i32 s0, s0, s40
	s_lshl_b32 s41, s79, 4
	ds_write_b128 v64, v[56:59]
	ds_write_b128 v64, v[60:63] offset:64
	ds_write_b128 v64, v[48:51] offset:128
	ds_write_b128 v64, v[52:55] offset:192
	s_mul_hi_i32 s40, s0, 0x600
	s_mulk_i32 s0, 0x600
	s_and_b32 s41, s41, 0xffffff80
	v_ashrrev_i32_e32 v71, 3, v66
	s_waitcnt lgkmcnt(0)
	ds_write_b128 v64, v[40:43] offset:4352
	ds_write_b128 v64, v[44:47] offset:4416
	ds_write_b128 v64, v[32:35] offset:4480
	ds_write_b128 v64, v[36:39] offset:4544
	v_mov_b32_e32 v64, s0
	v_mov_b32_e32 v65, s40
	s_movk_i32 s0, 0x600
	s_add_i32 s60, s41, 0xffffea00
	v_mad_i64_i32 v[64:65], s[40:41], v71, s0, v[64:65]
	v_and_b32_e32 v77, 7, v66
	s_waitcnt lgkmcnt(0)
	v_lshl_or_b32 v64, v77, 4, v64
	v_lshl_add_u64 v[64:65], s[60:61], 1, v[64:65]
	v_mul_lo_u32 v71, v71, s77
	v_lshlrev_b32_e32 v77, 5, v77
	v_lshl_add_u64 v[66:67], s[10:11], 0, v[64:65]
	v_add3_u32 v71, v71, v77, s73
	s_mov_b32 s0, 0
.LBB0_1394:
	v_add_u32_e32 v77, s0, v71
	v_add_u32_e32 v80, 0x10000, v77
	v_add_u32_e32 v77, 0x10010, v77
	ds_read_b128 v[82:85], v80
	ds_read_b128 v[86:89], v77
	s_addk_i32 s0, 0x880
	s_cmpk_lg_i32 s0, 0x2200
	s_waitcnt lgkmcnt(0)
	v_cvt_pk_bf16_f32 v82, v82, v83
	v_cvt_pk_bf16_f32 v83, v84, v85
	v_cvt_pk_bf16_f32 v84, v86, v87
	v_cvt_pk_bf16_f32 v85, v88, v89
	global_store_dwordx4 v[66:67], v[82:85], off sc1
	s_nop 1
	v_lshl_add_u64 v[66:67], v[66:67], 0, s[20:21]
	s_cbranch_scc1 .LBB0_1394
	v_add_u32_e32 v66, v73, v75
	ds_write_b128 v66, v[24:27]
	ds_write_b128 v66, v[28:31] offset:64
	ds_write_b128 v66, v[16:19] offset:128
	ds_write_b128 v66, v[20:23] offset:192
	s_nop 1
	ds_write_b128 v66, v[8:11] offset:4352
	ds_write_b128 v66, v[12:15] offset:4416
	ds_write_b128 v66, v[0:3] offset:4480
	ds_write_b128 v66, v[4:7] offset:4544
	s_nop 1
	v_lshl_add_u64 v[64:65], s[12:13], 0, v[64:65]
	s_mov_b32 s0, 0

.LBB0_1398:
	s_and_b64 vcc, exec, s[40:41]
	s_cbranch_vccz .LBB0_1403
	v_mov_b32_e32 v66, v188
	s_waitcnt lgkmcnt(0)
	s_lshl_b32 s0, s79, 3
	v_and_b32_e32 v65, -16, v66
	v_and_b32_e32 v64, 15, v66
	v_add_u32_e32 v73, s78, v65
	v_mul_u32_u24_e32 v75, 0x110, v64
	v_mad_u32_u24 v64, v64, s77, v73
	ds_write_b128 v64, v[56:59]
	ds_write_b128 v64, v[60:63] offset:64
	ds_write_b128 v64, v[48:51] offset:128
	ds_write_b128 v64, v[52:55] offset:192
	s_nop 1
	ds_write_b128 v64, v[40:43] offset:4352
	ds_write_b128 v64, v[44:47] offset:4416
	ds_write_b128 v64, v[32:35] offset:4480
	ds_write_b128 v64, v[36:39] offset:4544
	s_and_b32 s0, s0, 0xf00
	v_ashrrev_i32_e32 v71, 3, v66
	s_waitcnt lgkmcnt(0)
	v_mov_b32_e32 v80, s0
	s_movk_i32 s0, 0x600
	v_mad_i64_i32 v[64:65], s[40:41], v71, s0, v[80:81]
	v_and_b32_e32 v77, 7, v66
	v_lshl_or_b32 v64, v77, 4, v64
	v_mul_lo_u32 v71, v71, s77
	v_lshlrev_b32_e32 v77, 5, v77
	v_lshl_add_u64 v[66:67], s[18:19], 0, v[64:65]
	v_add3_u32 v71, v71, v77, s73
	s_mov_b32 s0, 0
.LBB0_1400:
	v_add_u32_e32 v77, s0, v71
	v_add_u32_e32 v80, 0x10000, v77
	v_add_u32_e32 v77, 0x10010, v77
	ds_read_b128 v[82:85], v80
	ds_read_b128 v[86:89], v77
	s_addk_i32 s0, 0x880
	s_cmpk_lg_i32 s0, 0x2200
	s_waitcnt lgkmcnt(0)
	v_cvt_pk_bf16_f32 v82, v82, v83
	v_cvt_pk_bf16_f32 v83, v84, v85
	v_cvt_pk_bf16_f32 v84, v86, v87
	v_cvt_pk_bf16_f32 v85, v88, v89
	global_store_dwordx4 v[66:67], v[82:85], off sc1
	s_nop 1
	v_lshl_add_u64 v[66:67], v[66:67], 0, s[20:21]
	s_cbranch_scc1 .LBB0_1400
	v_add_u32_e32 v66, v73, v75
	ds_write_b128 v66, v[24:27]
	ds_write_b128 v66, v[28:31] offset:64
	ds_write_b128 v66, v[16:19] offset:128
	ds_write_b128 v66, v[20:23] offset:192
	s_nop 1
	ds_write_b128 v66, v[8:11] offset:4352
	ds_write_b128 v66, v[12:15] offset:4416
	ds_write_b128 v66, v[0:3] offset:4480
	ds_write_b128 v66, v[4:7] offset:4544
	s_nop 1
	v_lshl_add_u64 v[64:65], s[26:27], 0, v[64:65]
	s_mov_b32 s0, 0

.LBB0_1411:
	v_and_b32_e32 v60, -16, v109
	v_or_b32_e32 v63, 16, v80
	v_add_u32_e32 v62, s78, v60
	v_or_b32_e32 v60, v63, v206
	v_lshlrev_b32_e32 v60, 2, v60
	ds_bpermute_b32 v60, v60, v106
	v_mad_u32_u24 v61, v80, s77, v62
	ds_write_b128 v61, v[64:67]
	ds_write_b128 v61, v[56:59] offset:64
	ds_write_b128 v61, v[48:51] offset:128
	ds_write_b128 v61, v[52:55] offset:192
	s_waitcnt lgkmcnt(0)
	v_pk_mul_f32 v[50:51], v[42:43], v[60:61] op_sel_hi:[1,0]
	v_pk_mul_f32 v[42:43], v[46:47], v[60:61] op_sel_hi:[1,0]
	v_cvt_f32_ubyte0_e32 v46, v63
	v_pk_mul_f32 v[48:49], v[40:41], v[60:61] op_sel_hi:[1,0]
	v_pk_mul_f32 v[40:41], v[44:45], v[60:61] op_sel_hi:[1,0]
	v_mul_f32_e32 v45, v77, v46
	v_sin_f32_e32 v47, v45
	v_mul_f32_e32 v44, v75, v46
	v_sin_f32_e32 v52, v44
	v_cos_f32_e32 v44, v44
	v_cndmask_b32_e64 v53, -v47, v47, s[42:43]
	v_mul_f32_e32 v47, v108, v46
	v_mul_f32_e32 v46, v107, v46
	v_sin_f32_e32 v55, v47
	v_cos_f32_e32 v54, v47
	v_sin_f32_e32 v47, v46
	v_cos_f32_e32 v45, v45
	v_cos_f32_e32 v46, v46
	s_waitcnt lgkmcnt(0)
	v_cndmask_b32_e64 v52, -v52, v52, s[42:43]
	v_cndmask_b32_e64 v55, -v55, v55, s[42:43]
	s_and_b64 vcc, exec, s[40:41]
	v_cndmask_b32_e64 v47, -v47, v47, s[42:43]
	s_cbranch_vccnz .LBB0_1414
	s_ashr_i32 s0, s44, 5
	s_mul_hi_i32 s45, s0, 0x55555556
	s_lshr_b32 s46, s45, 31
	s_add_i32 s45, s45, s46
	s_mul_i32 s45, s45, 3
	s_sub_i32 s0, s0, s45
	s_cmp_lg_u32 s0, 2
	s_cbranch_scc1 .LBB0_1414
	ds_bpermute_b32 v56, v219, v48
	ds_bpermute_b32 v57, v219, v49
	ds_bpermute_b32 v65, v219, v51
	ds_bpermute_b32 v91, v219, v43
	ds_bpermute_b32 v58, v219, v40
	ds_bpermute_b32 v59, v219, v41
	ds_bpermute_b32 v61, v219, v50
	ds_bpermute_b32 v63, v219, v42
	s_waitcnt lgkmcnt(0)
	v_pk_mul_f32 v[56:57], v[86:87], v[56:57]
	v_mov_b32_e32 v64, v51
	v_mov_b32_e32 v90, v43
	v_pk_mul_f32 v[64:65], v[84:85], v[64:65]
	v_pk_fma_f32 v[48:49], v[82:83], v[48:49], v[56:57]
	v_pk_mul_f32 v[56:57], v[46:47], v[90:91]
	v_pk_mul_f32 v[58:59], v[52:53], v[58:59]
	v_mul_f32_e32 v50, v71, v50
	v_mul_f32_e32 v66, v73, v61
	v_mul_f32_e32 v42, v54, v42
	v_mul_f32_e32 v88, v55, v63
	v_mov_b32_e32 v51, v64
	v_mov_b32_e32 v67, v65
	v_mov_b32_e32 v43, v56
	v_mov_b32_e32 v89, v57
	v_pk_add_f32 v[50:51], v[50:51], v[66:67]
	v_pk_fma_f32 v[40:41], v[44:45], v[40:41], v[58:59]
	v_pk_add_f32 v[42:43], v[42:43], v[88:89]

.LBB0_1417:
	v_mul_u32_u24_e32 v44, 0x110, v80
	v_ashrrev_i32_e32 v45, 3, v109
	v_add_u32_e32 v44, v44, v62
	s_movk_i32 s0, 0x480
	ds_write_b128 v44, v[48:51] offset:4352
	ds_write_b128 v44, v[40:43] offset:4416
	ds_write_b128 v44, v[32:35] offset:4480
	ds_write_b128 v44, v[36:39] offset:4544
	v_mad_i64_i32 v[32:33], s[46:47], v45, s0, 0
	v_and_b32_e32 v34, 7, v109
	s_ashr_i32 s45, s44, 31
	s_waitcnt lgkmcnt(0)
	v_lshl_or_b32 v32, v34, 4, v32
	v_lshl_add_u64 v[36:37], s[44:45], 1, v[32:33]
	v_mul_lo_u32 v35, v45, s77
	v_lshlrev_b32_e32 v34, 5, v34
	v_lshl_add_u64 v[32:33], s[28:29], 0, v[36:37]
	v_add3_u32 v42, v35, v34, s73
	s_mov_b32 s0, 0

.LBB0_1425:
	v_or_b32_e32 v29, 48, v80
	v_or_b32_e32 v28, v29, v206
	v_lshlrev_b32_e32 v28, 2, v28
	ds_bpermute_b32 v28, v28, v106
	ds_write_b128 v44, v[32:35]
	ds_write_b128 v44, v[24:27] offset:64
	ds_write_b128 v44, v[16:19] offset:128
	ds_write_b128 v44, v[20:23] offset:192
	s_nop 1
	s_waitcnt lgkmcnt(0)
	v_pk_mul_f32 v[18:19], v[10:11], v[28:29] op_sel_hi:[1,0]
	v_pk_mul_f32 v[10:11], v[14:15], v[28:29] op_sel_hi:[1,0]
	v_cvt_f32_ubyte0_e32 v14, v29
	v_pk_mul_f32 v[16:17], v[8:9], v[28:29] op_sel_hi:[1,0]
	v_pk_mul_f32 v[8:9], v[12:13], v[28:29] op_sel_hi:[1,0]
	v_mul_f32_e32 v13, v77, v14
	v_sin_f32_e32 v15, v13
	v_mul_f32_e32 v12, v75, v14
	v_sin_f32_e32 v20, v12
	v_cos_f32_e32 v12, v12
	v_cndmask_b32_e64 v21, -v15, v15, s[42:43]
	v_mul_f32_e32 v15, v108, v14
	v_mul_f32_e32 v14, v107, v14
	v_sin_f32_e32 v23, v15
	v_cos_f32_e32 v22, v15
	v_sin_f32_e32 v15, v14
	v_cos_f32_e32 v13, v13
	v_cos_f32_e32 v14, v14
	v_cndmask_b32_e64 v20, -v20, v20, s[42:43]
	v_cndmask_b32_e64 v23, -v23, v23, s[42:43]
	s_and_b64 vcc, exec, s[40:41]
	v_cndmask_b32_e64 v15, -v15, v15, s[42:43]
	s_cbranch_vccnz .LBB0_1428
	s_ashr_i32 s0, s44, 5
	s_mul_hi_i32 s42, s0, 0x55555556
	s_lshr_b32 s43, s42, 31
	s_add_i32 s42, s42, s43
	s_mul_i32 s42, s42, 3
	s_sub_i32 s0, s0, s42
	s_cmp_lg_u32 s0, 2
	s_cbranch_scc1 .LBB0_1428
	ds_bpermute_b32 v24, v219, v16
	ds_bpermute_b32 v25, v219, v17
	ds_bpermute_b32 v30, v219, v10
	ds_bpermute_b32 v31, v219, v19
	ds_bpermute_b32 v39, v219, v11
	ds_bpermute_b32 v26, v219, v8
	ds_bpermute_b32 v27, v219, v9
	ds_bpermute_b32 v29, v219, v18
	s_waitcnt lgkmcnt(0)
	v_pk_mul_f32 v[24:25], v[86:87], v[24:25]
	v_mul_f32_e32 v34, v23, v30
	v_mov_b32_e32 v30, v19
	v_mov_b32_e32 v38, v11
	v_pk_mul_f32 v[30:31], v[84:85], v[30:31]
	v_pk_fma_f32 v[16:17], v[82:83], v[16:17], v[24:25]
	v_pk_mul_f32 v[24:25], v[14:15], v[38:39]
	v_pk_mul_f32 v[26:27], v[20:21], v[26:27]
	v_mul_f32_e32 v18, v71, v18
	v_mul_f32_e32 v32, v73, v29
	v_mul_f32_e32 v10, v22, v10
	v_mov_b32_e32 v19, v30
	v_mov_b32_e32 v33, v31
	v_mov_b32_e32 v11, v24
	v_mov_b32_e32 v35, v25
	v_pk_add_f32 v[18:19], v[18:19], v[32:33]
	v_pk_fma_f32 v[8:9], v[12:13], v[8:9], v[26:27]
	v_pk_add_f32 v[10:11], v[10:11], v[34:35]

.LBB0_1431:
	ds_write_b128 v44, v[16:19] offset:4352
	ds_write_b128 v44, v[8:11] offset:4416
	ds_write_b128 v44, v[0:3] offset:4480
	ds_write_b128 v44, v[4:7] offset:4544
	s_nop 1
	v_lshl_add_u64 v[0:1], s[34:35], 0, v[36:37]
	s_mov_b32 s0, 0
